# PG (EpiPle) epilogue: keep 3 chunks (6 x4 loads) in flight via pool in dead K-loop fragment regs v192-215, saddr addressing, counted vmcnt; rest = v028
# baseline (speedup 1.0000x reference)
; #define GAS __attribute__((address_space(1)))
; __device__ __forceinline__ unsigned cvt_pk_bf16(float lo, float hi) { unsigned r; asm volatile("v_cvt_pk_bf16_f32 %0, %1, %2" : "=v"(r) : "v"(lo), "v"(hi)); return r; }
; __device__ __forceinline__ float bf_lo(unsigned w) { return __uint_as_float(w << 16); }
; __device__ __forceinline__ float bf_hi(unsigned w) { return __uint_as_float(w & 0xffff0000u); }
;     __device__ __forceinline__ void operator()(const f32x4 (&acc)[2][2][4][2], const Unit& u, int wr, int wc, int fr, int fq) const {
;     ...
;         for (int bj = 0; bj < 2; ++bj) { bv[bj][0] = *(const GAS f32x4*)(bias + col0 + bj * HALF); bv[bj][1] = *(const GAS f32x4*)(bias + col0 + bj * HALF + 4); }
; #pragma unroll
;         for (int ai = 0; ai < 2; ++ai)
; #pragma unroll
;             for (int m = 0; m < 4; ++m) { const size_t off = (size_t)(row0 + ai * HALF + m * 16) * DM + col0; q[ai][m] = 0.f;
; #pragma unroll
;                 for (int bj = 0; bj < 2; ++bj) { const u32x4 bw = *(const GAS u32x4*)(baseb + off + bj * HALF);
;                     const f32x4 b0 = {bf_lo(bw.x), bf_hi(bw.x), bf_lo(bw.y), bf_hi(bw.y)}, b1 = {bf_lo(bw.z), bf_hi(bw.z), bf_lo(bw.w), bf_hi(bw.w)};
;                     const u32x4 pw = *(const GAS u32x4*)(pp + off + bj * HALF);
;                     const f32x4 p0 = {bf_lo(pw.x), bf_hi(pw.x), bf_lo(pw.y), bf_hi(pw.y)}, p1 = {bf_lo(pw.z), bf_hi(pw.z), bf_lo(pw.w), bf_hi(pw.w)};
;                     const f32x4 z0 = acc[ai][bj][m][0] + bv[bj][0], z1 = acc[ai][bj][m][1] + bv[bj][1]; f32x4 g0, g1;
; #pragma unroll
;                     for (int i = 0; i < 4; ++i) { g0[i] = __builtin_amdgcn_rcpf(1.f + __expf(-z0[i])); g1[i] = __builtin_amdgcn_rcpf(1.f + __expf(-z1[i])); }
;                     const f32x4 o0 = b0 + g0 * p0, o1 = b1 + g1 * p1;
;                     if (out) { *(GAS f32x4*)(out + off + bj * HALF) = o0; *(GAS f32x4*)(out + off + bj * HALF + 4) = o1; }
;                     if (xb) { q[ai][m] += (o0[0] * o0[0] + o0[1] * o0[1]) + (o0[2] * o0[2] + o0[3] * o0[3]) + (o1[0] * o1[0] + o1[1] * o1[1]) + (o1[2] * o1[2] + o1[3] * o1[3]);
;                         u32x4 w; w.x = cvt_pk_bf16(o0[0], o0[1]); w.y = cvt_pk_bf16(o0[2], o0[3]); w.z = cvt_pk_bf16(o1[0], o1[1]); w.w = cvt_pk_bf16(o1[2], o1[3]); *(GAS u32x4*)(xb + off + bj * HALF) = w; } } }
.LBB0_894:
	v_lshl_or_b32 v158, s54, 8, v168
	v_ashrrev_i32_e32 v159, 31, v158
	v_lshl_add_u64 v[28:29], v[158:159], 2, s[16:17]
	global_load_dwordx4 v[44:47], v[28:29], off
	global_load_dwordx4 v[40:43], v[28:29], off offset:16
	v_lshl_add_u32 v154, s53, 8, v164
	v_ashrrev_i32_e32 v155, 31, v154
	v_lshlrev_b64 v[24:25], 11, v[154:155]
	v_lshl_add_u64 v[24:25], v[24:25], 0, v[158:159]
	v_lshlrev_b64 v[156:157], 1, v[24:25]
	v_lshl_add_u64 v[174:175], s[34:35], 0, v[156:157]
	v_lshl_add_u64 v[178:179], s[30:31], 0, v[156:157]
	global_load_dwordx4 v[24:27], v[28:29], off offset:528
	s_nop 0
	global_load_dwordx4 v[28:31], v[28:29], off offset:512
	global_load_dwordx4 v[192:195], v156, s[34:35]
	global_load_dwordx4 v[196:199], v156, s[30:31]
	global_load_dwordx4 v[200:203], v156, s[34:35] offset:256
	global_load_dwordx4 v[204:207], v156, s[30:31] offset:256
	s_add_u32 vcc_lo, s34, 0x10000
	s_addc_u32 vcc_hi, s35, 0
	global_load_dwordx4 v[208:211], v156, vcc
	s_add_u32 vcc_lo, s30, 0x10000
	s_addc_u32 vcc_hi, s31, 0
	global_load_dwordx4 v[212:215], v156, vcc
	s_mov_b64 s[40:41], 0x80000
	s_waitcnt vmcnt(4)
	v_mov_b32_e32 v160, v192
	v_mov_b32_e32 v161, v193
	v_mov_b32_e32 v162, v194
	v_mov_b32_e32 v163, v195
	v_mov_b32_e32 v170, v196
	v_mov_b32_e32 v171, v197
	v_mov_b32_e32 v172, v198
	v_mov_b32_e32 v173, v199
	s_add_u32 vcc_lo, s34, 0x10000
	s_addc_u32 vcc_hi, s35, 0
	global_load_dwordx4 v[192:195], v156, vcc offset:256
	s_add_u32 vcc_lo, s30, 0x10000
	s_addc_u32 vcc_hi, s31, 0
	global_load_dwordx4 v[196:199], v156, vcc offset:256
	v_add_f32_e32 v140, v140, v44
	v_add_f32_e32 v136, v136, v40
	v_add_f32_e32 v141, v141, v45
	v_add_f32_e32 v137, v137, v41
	v_add_f32_e32 v142, v142, v46
	v_add_f32_e32 v138, v138, v42
	v_add_f32_e32 v143, v143, v47
	v_add_f32_e32 v139, v139, v43
	v_mul_f32_e32 v140, 0xbfb8aa3b, v140
	v_mul_f32_e32 v136, 0xbfb8aa3b, v136
	v_mul_f32_e32 v141, 0xbfb8aa3b, v141
	v_mul_f32_e32 v137, 0xbfb8aa3b, v137
	v_mul_f32_e32 v142, 0xbfb8aa3b, v142
	v_mul_f32_e32 v138, 0xbfb8aa3b, v138
	v_mul_f32_e32 v143, 0xbfb8aa3b, v143
	v_mul_f32_e32 v139, 0xbfb8aa3b, v139
	v_exp_f32_e32 v176, v140
	v_exp_f32_e32 v177, v136
	v_exp_f32_e32 v180, v141
	v_exp_f32_e32 v181, v137
	v_exp_f32_e32 v182, v142
	v_exp_f32_e32 v183, v138
	v_exp_f32_e32 v186, v143
	v_exp_f32_e32 v187, v139
	v_add_f32_e32 v176, 1.0, v176
	v_add_f32_e32 v177, 1.0, v177
	v_add_f32_e32 v188, 1.0, v180
	v_add_f32_e32 v181, 1.0, v181
	v_add_f32_e32 v182, 1.0, v182
	v_add_f32_e32 v189, 1.0, v183
	v_add_f32_e32 v183, 1.0, v186
	v_add_f32_e32 v186, 1.0, v187
	v_rcp_f32_e32 v176, v176
	v_rcp_f32_e32 v180, v177
	v_rcp_f32_e32 v177, v188
	v_rcp_f32_e32 v182, v182
	v_rcp_f32_e32 v183, v183
	v_rcp_f32_e32 v188, v189
	v_rcp_f32_e32 v189, v186
	v_rcp_f32_e32 v181, v181
	v_lshlrev_b32_e32 v138, 16, v160
	v_and_b32_e32 v139, 0xffff0000, v160
	v_lshlrev_b32_e32 v136, 16, v161
	v_and_b32_e32 v137, 0xffff0000, v161
	v_lshlrev_b32_e32 v142, 16, v162
	v_and_b32_e32 v143, 0xffff0000, v162
	v_lshlrev_b32_e32 v140, 16, v163
	v_and_b32_e32 v141, 0xffff0000, v163
	v_lshlrev_b32_e32 v160, 16, v170
	v_and_b32_e32 v161, 0xffff0000, v170
	v_lshlrev_b32_e32 v162, 16, v171
	v_and_b32_e32 v163, 0xffff0000, v171
	v_lshlrev_b32_e32 v170, 16, v172
	v_and_b32_e32 v171, 0xffff0000, v172
	v_lshlrev_b32_e32 v172, 16, v173
	v_and_b32_e32 v173, 0xffff0000, v173
	v_pk_fma_f32 v[136:137], v[182:183], v[162:163], v[136:137]
	v_pk_fma_f32 v[138:139], v[176:177], v[160:161], v[138:139]
	v_pk_fma_f32 v[140:141], v[188:189], v[172:173], v[140:141]
	v_pk_fma_f32 v[142:143], v[180:181], v[170:171], v[142:143]
	v_cvt_pk_bf16_f32 v170, v138, v139
	v_cvt_pk_bf16_f32 v171, v136, v137
	v_add_f32_e32 v132, v132, v28
	v_cvt_pk_bf16_f32 v172, v142, v143
	v_cvt_pk_bf16_f32 v173, v140, v141
	s_nop 0
	v_add_f32_e32 v128, v128, v24
	v_add_f32_e32 v133, v133, v29
	v_add_f32_e32 v129, v129, v25
	v_add_f32_e32 v134, v134, v30
	v_add_f32_e32 v130, v130, v26
	v_add_f32_e32 v135, v135, v31
	v_add_f32_e32 v131, v131, v27
	v_mul_f32_e32 v132, 0xbfb8aa3b, v132
	v_mul_f32_e32 v128, 0xbfb8aa3b, v128
	v_mul_f32_e32 v133, 0xbfb8aa3b, v133
	v_mul_f32_e32 v129, 0xbfb8aa3b, v129
	v_mul_f32_e32 v134, 0xbfb8aa3b, v134
	v_mul_f32_e32 v130, 0xbfb8aa3b, v130
	v_mul_f32_e32 v135, 0xbfb8aa3b, v135
	v_mul_f32_e32 v131, 0xbfb8aa3b, v131
	v_exp_f32_e32 v132, v132
	v_exp_f32_e32 v128, v128
	v_exp_f32_e32 v133, v133
	v_exp_f32_e32 v129, v129
	v_exp_f32_e32 v134, v134
	v_exp_f32_e32 v130, v130
	v_exp_f32_e32 v135, v135
	v_exp_f32_e32 v131, v131
	v_or_b32_e32 v160, 16, v154
	v_add_f32_e32 v132, 1.0, v132
	v_add_f32_e32 v128, 1.0, v128
	v_add_f32_e32 v133, 1.0, v133
	v_add_f32_e32 v129, 1.0, v129
	v_add_f32_e32 v186, 1.0, v134
	v_add_f32_e32 v187, 1.0, v130
	v_add_f32_e32 v189, 1.0, v135
	v_add_f32_e32 v190, 1.0, v131
	v_ashrrev_i32_e32 v161, 31, v160
	v_rcp_f32_e32 v130, v132
	v_rcp_f32_e32 v134, v128
	v_rcp_f32_e32 v131, v133
	v_rcp_f32_e32 v135, v129
	v_rcp_f32_e32 v128, v186
	v_rcp_f32_e32 v188, v187
	v_rcp_f32_e32 v129, v189
	v_rcp_f32_e32 v189, v190
	v_lshlrev_b64 v[160:161], 11, v[160:161]
	v_lshl_add_u64 v[160:161], v[160:161], 0, v[158:159]
	v_lshl_add_u64 v[182:183], s[96:97], 0, v[156:157]
	v_lshlrev_b64 v[162:163], 1, v[160:161]
	global_store_dwordx4 v[182:183], v[170:173], off
	s_nop 3
	v_lshl_add_u64 v[160:161], s[34:35], 0, v[162:163]
	v_add_f32_e32 v124, v124, v44
	v_add_f32_e32 v120, v120, v40
	v_add_f32_e32 v125, v125, v45
	v_add_f32_e32 v121, v121, v41
	v_add_f32_e32 v126, v126, v46
	v_add_f32_e32 v122, v122, v42
	v_add_f32_e32 v127, v127, v47
	v_add_f32_e32 v123, v123, v43
	v_mul_f32_e32 v124, 0xbfb8aa3b, v124
	v_mul_f32_e32 v120, 0xbfb8aa3b, v120
	v_mul_f32_e32 v125, 0xbfb8aa3b, v125
	v_mul_f32_e32 v121, 0xbfb8aa3b, v121
	v_mul_f32_e32 v126, 0xbfb8aa3b, v126
	v_mul_f32_e32 v122, 0xbfb8aa3b, v122
	v_mul_f32_e32 v127, 0xbfb8aa3b, v127
	v_mul_f32_e32 v123, 0xbfb8aa3b, v123
	v_exp_f32_e32 v124, v124
	v_exp_f32_e32 v120, v120
	v_exp_f32_e32 v125, v125
	v_exp_f32_e32 v121, v121
	v_exp_f32_e32 v126, v126
	v_exp_f32_e32 v122, v122
	v_exp_f32_e32 v127, v127
	v_exp_f32_e32 v123, v123
	v_add_f32_e32 v124, 1.0, v124
	v_add_f32_e32 v120, 1.0, v120
	v_add_f32_e32 v125, 1.0, v125
	v_add_f32_e32 v121, 1.0, v121
	v_add_f32_e32 v116, v116, v28
	v_add_f32_e32 v112, v112, v24
	v_add_f32_e32 v117, v117, v29
	s_waitcnt vmcnt(5)
; #define GAS __attribute__((address_space(1)))
; __device__ __forceinline__ unsigned cvt_pk_bf16(float lo, float hi) { unsigned r; asm volatile("v_cvt_pk_bf16_f32 %0, %1, %2" : "=v"(r) : "v"(lo), "v"(hi)); return r; }
; __device__ __forceinline__ float bf_lo(unsigned w) { return __uint_as_float(w << 16); }
; __device__ __forceinline__ float bf_hi(unsigned w) { return __uint_as_float(w & 0xffff0000u); }
;     __device__ __forceinline__ void operator()(const f32x4 (&acc)[2][2][4][2], const Unit& u, int wr, int wc, int fr, int fq) const {
;     ...
;             for (int m = 0; m < 4; ++m) { const size_t off = (size_t)(row0 + ai * HALF + m * 16) * DM + col0; q[ai][m] = 0.f;
; #pragma unroll
;                 for (int bj = 0; bj < 2; ++bj) { const u32x4 bw = *(const GAS u32x4*)(baseb + off + bj * HALF);
;                     const f32x4 b0 = {bf_lo(bw.x), bf_hi(bw.x), bf_lo(bw.y), bf_hi(bw.y)}, b1 = {bf_lo(bw.z), bf_hi(bw.z), bf_lo(bw.w), bf_hi(bw.w)};
;                     const u32x4 pw = *(const GAS u32x4*)(pp + off + bj * HALF);
;                     const f32x4 p0 = {bf_lo(pw.x), bf_hi(pw.x), bf_lo(pw.y), bf_hi(pw.y)}, p1 = {bf_lo(pw.z), bf_hi(pw.z), bf_lo(pw.w), bf_hi(pw.w)};
;                     const f32x4 z0 = acc[ai][bj][m][0] + bv[bj][0], z1 = acc[ai][bj][m][1] + bv[bj][1]; f32x4 g0, g1;
; #pragma unroll
;                     for (int i = 0; i < 4; ++i) { g0[i] = __builtin_amdgcn_rcpf(1.f + __expf(-z0[i])); g1[i] = __builtin_amdgcn_rcpf(1.f + __expf(-z1[i])); }
;                     const f32x4 o0 = b0 + g0 * p0, o1 = b1 + g1 * p1;
;                     if (out) { *(GAS f32x4*)(out + off + bj * HALF) = o0; *(GAS f32x4*)(out + off + bj * HALF + 4) = o1; }
;                     if (xb) { q[ai][m] += (o0[0] * o0[0] + o0[1] * o0[1]) + (o0[2] * o0[2] + o0[3] * o0[3]) + (o1[0] * o1[0] + o1[1] * o1[1]) + (o1[2] * o1[2] + o1[3] * o1[3]);
;                         u32x4 w; w.x = cvt_pk_bf16(o0[0], o0[1]); w.y = cvt_pk_bf16(o0[2], o0[3]); w.z = cvt_pk_bf16(o1[0], o1[1]); w.w = cvt_pk_bf16(o1[2], o1[3]); *(GAS u32x4*)(xb + off + bj * HALF) = w; } } }
	v_mov_b32_e32 v174, v200
	v_mov_b32_e32 v175, v201
	v_mov_b32_e32 v176, v202
	v_mov_b32_e32 v177, v203
	v_mov_b32_e32 v178, v204
	v_mov_b32_e32 v179, v205
	v_mov_b32_e32 v180, v206
	v_mov_b32_e32 v181, v207
	s_add_u32 vcc_lo, s34, 0x20000
	s_addc_u32 vcc_hi, s35, 0
	global_load_dwordx4 v[200:203], v156, vcc
	s_add_u32 vcc_lo, s30, 0x20000
	s_addc_u32 vcc_hi, s31, 0
	global_load_dwordx4 v[204:207], v156, vcc
	v_lshlrev_b32_e32 v132, 16, v174
	v_and_b32_e32 v133, 0xffff0000, v174
	v_lshlrev_b32_e32 v170, 16, v175
	v_and_b32_e32 v171, 0xffff0000, v175
	v_lshlrev_b32_e32 v172, 16, v176
	v_and_b32_e32 v173, 0xffff0000, v176
	v_lshlrev_b32_e32 v174, 16, v177
	v_and_b32_e32 v175, 0xffff0000, v177
	v_lshlrev_b32_e32 v176, 16, v178
	v_and_b32_e32 v177, 0xffff0000, v178
	v_lshlrev_b32_e32 v178, 16, v179
	v_and_b32_e32 v179, 0xffff0000, v179
	v_lshlrev_b32_e32 v190, 16, v180
	v_and_b32_e32 v191, 0xffff0000, v180
	v_lshlrev_b32_e32 v180, 16, v181
	v_and_b32_e32 v181, 0xffff0000, v181
	v_pk_fma_f32 v[128:129], v[128:129], v[178:179], v[170:171]
	v_pk_fma_f32 v[132:133], v[130:131], v[176:177], v[132:133]
	v_pk_fma_f32 v[130:131], v[188:189], v[180:181], v[174:175]
	v_pk_fma_f32 v[134:135], v[134:135], v[190:191], v[172:173]
	v_cvt_pk_bf16_f32 v170, v132, v133
	v_cvt_pk_bf16_f32 v171, v128, v129
	v_lshl_add_u64 v[178:179], s[30:31], 0, v[162:163]
	v_cvt_pk_bf16_f32 v172, v134, v135
	v_cvt_pk_bf16_f32 v173, v130, v131
	global_store_dwordx4 v[182:183], v[170:173], off offset:256
	s_nop 3
	v_add_f32_e32 v180, 1.0, v126
	v_add_f32_e32 v181, 1.0, v122
	v_add_f32_e32 v182, 1.0, v127
	v_add_f32_e32 v183, 1.0, v123
	v_rcp_f32_e32 v122, v124
	v_rcp_f32_e32 v126, v120
	v_rcp_f32_e32 v123, v125
	v_rcp_f32_e32 v127, v121
	v_rcp_f32_e32 v120, v180
	v_rcp_f32_e32 v180, v181
	v_rcp_f32_e32 v121, v182
	v_rcp_f32_e32 v181, v183
	v_add_f32_e32 v113, v113, v25
	v_add_f32_e32 v118, v118, v30
	v_add_f32_e32 v114, v114, v26
	v_add_f32_e32 v119, v119, v31
	v_add_f32_e32 v115, v115, v27
	v_mul_f32_e32 v116, 0xbfb8aa3b, v116
	v_mul_f32_e32 v112, 0xbfb8aa3b, v112
	v_mul_f32_e32 v117, 0xbfb8aa3b, v117
	v_mul_f32_e32 v113, 0xbfb8aa3b, v113
	v_mul_f32_e32 v118, 0xbfb8aa3b, v118
	v_mul_f32_e32 v114, 0xbfb8aa3b, v114
	v_mul_f32_e32 v119, 0xbfb8aa3b, v119
	v_mul_f32_e32 v115, 0xbfb8aa3b, v115
	v_exp_f32_e32 v116, v116
	v_exp_f32_e32 v112, v112
	v_exp_f32_e32 v117, v117
	v_exp_f32_e32 v113, v113
	v_exp_f32_e32 v118, v118
	v_exp_f32_e32 v114, v114
	v_exp_f32_e32 v119, v119
	v_exp_f32_e32 v115, v115
	v_add_f32_e32 v116, 1.0, v116
	v_add_f32_e32 v186, 1.0, v112
	v_add_f32_e32 v117, 1.0, v117
	v_add_f32_e32 v187, 1.0, v113
	v_add_f32_e32 v118, 1.0, v118
	v_add_f32_e32 v119, 1.0, v119
	v_rcp_f32_e32 v112, v116
	v_rcp_f32_e32 v113, v117
	v_rcp_f32_e32 v116, v118
	v_rcp_f32_e32 v117, v119
	v_lshl_add_u64 v[162:163], s[96:97], 0, v[162:163]
	v_add_f32_e32 v108, v108, v44
	v_add_f32_e32 v104, v104, v40
	v_add_f32_e32 v109, v109, v45
	v_add_f32_e32 v105, v105, v41
	v_add_f32_e32 v110, v110, v46
	v_add_f32_e32 v106, v106, v42
	v_add_f32_e32 v111, v111, v47
	v_add_f32_e32 v107, v107, v43
	v_mul_f32_e32 v108, 0xbfb8aa3b, v108
	v_mul_f32_e32 v104, 0xbfb8aa3b, v104
	v_mul_f32_e32 v109, 0xbfb8aa3b, v109
	v_mul_f32_e32 v105, 0xbfb8aa3b, v105
	v_mul_f32_e32 v110, 0xbfb8aa3b, v110
	v_mul_f32_e32 v106, 0xbfb8aa3b, v106
	v_mul_f32_e32 v111, 0xbfb8aa3b, v111
	v_mul_f32_e32 v107, 0xbfb8aa3b, v107
	v_exp_f32_e32 v108, v108
	v_exp_f32_e32 v104, v104
	v_exp_f32_e32 v109, v109
	v_exp_f32_e32 v105, v105
	v_exp_f32_e32 v110, v110
	v_exp_f32_e32 v106, v106
	v_exp_f32_e32 v111, v111
	v_exp_f32_e32 v107, v107
	v_add_f32_e32 v108, 1.0, v108
	v_add_f32_e32 v104, 1.0, v104
	v_add_f32_e32 v109, 1.0, v109
	v_add_f32_e32 v105, 1.0, v105
	v_add_f32_e32 v100, v100, v28
	v_add_f32_e32 v96, v96, v24
	v_add_f32_e32 v101, v101, v29
	v_add_f32_e32 v97, v97, v25
	v_add_f32_e32 v102, v102, v30
	v_add_f32_e32 v98, v98, v26
	s_waitcnt vmcnt(6)
	v_mov_b32_e32 v170, v208
	v_mov_b32_e32 v171, v209
	v_mov_b32_e32 v172, v210
	v_mov_b32_e32 v173, v211
	v_mov_b32_e32 v174, v212
	v_mov_b32_e32 v175, v213
	v_mov_b32_e32 v176, v214
	v_mov_b32_e32 v177, v215
	s_add_u32 vcc_lo, s34, 0x20000
	s_addc_u32 vcc_hi, s35, 0
	global_load_dwordx4 v[208:211], v156, vcc offset:256
	s_add_u32 vcc_lo, s30, 0x20000
	s_addc_u32 vcc_hi, s31, 0
	global_load_dwordx4 v[212:215], v156, vcc offset:256
	v_lshlrev_b32_e32 v124, 16, v170
	v_and_b32_e32 v125, 0xffff0000, v170
	v_lshlrev_b32_e32 v170, 16, v171
	v_and_b32_e32 v171, 0xffff0000, v171
	v_lshlrev_b32_e32 v182, 16, v172
	v_and_b32_e32 v183, 0xffff0000, v172
	v_lshlrev_b32_e32 v172, 16, v173
	v_and_b32_e32 v173, 0xffff0000, v173
	v_lshlrev_b32_e32 v188, 16, v174
	v_and_b32_e32 v189, 0xffff0000, v174
	v_lshlrev_b32_e32 v174, 16, v175
	v_and_b32_e32 v175, 0xffff0000, v175
	v_lshlrev_b32_e32 v190, 16, v176
	v_and_b32_e32 v191, 0xffff0000, v176
	v_lshlrev_b32_e32 v176, 16, v177
	v_and_b32_e32 v177, 0xffff0000, v177
	v_pk_fma_f32 v[120:121], v[120:121], v[174:175], v[170:171]
	v_pk_fma_f32 v[124:125], v[122:123], v[188:189], v[124:125]
	v_pk_fma_f32 v[122:123], v[180:181], v[176:177], v[172:173]
	v_pk_fma_f32 v[126:127], v[126:127], v[190:191], v[182:183]
	v_cvt_pk_bf16_f32 v170, v124, v125
	v_cvt_pk_bf16_f32 v171, v120, v121
	v_add_f32_e32 v188, 1.0, v114
	v_cvt_pk_bf16_f32 v172, v126, v127
	v_cvt_pk_bf16_f32 v173, v122, v123
	s_nop 0
	v_or_b32_e32 v160, 32, v154
	v_add_f32_e32 v189, 1.0, v115
	v_ashrrev_i32_e32 v161, 31, v160
	v_rcp_f32_e32 v114, v186
	v_rcp_f32_e32 v115, v187
	v_rcp_f32_e32 v188, v188
	v_rcp_f32_e32 v189, v189
	v_lshlrev_b64 v[160:161], 11, v[160:161]
	v_lshl_add_u64 v[160:161], v[160:161], 0, v[158:159]
; #define GAS __attribute__((address_space(1)))
; __device__ __forceinline__ unsigned cvt_pk_bf16(float lo, float hi) { unsigned r; asm volatile("v_cvt_pk_bf16_f32 %0, %1, %2" : "=v"(r) : "v"(lo), "v"(hi)); return r; }
; __device__ __forceinline__ float bf_lo(unsigned w) { return __uint_as_float(w << 16); }
; __device__ __forceinline__ float bf_hi(unsigned w) { return __uint_as_float(w & 0xffff0000u); }
;     __device__ __forceinline__ void operator()(const f32x4 (&acc)[2][2][4][2], const Unit& u, int wr, int wc, int fr, int fq) const {
;     ...
;             for (int m = 0; m < 4; ++m) { const size_t off = (size_t)(row0 + ai * HALF + m * 16) * DM + col0; q[ai][m] = 0.f;
; #pragma unroll
;                 for (int bj = 0; bj < 2; ++bj) { const u32x4 bw = *(const GAS u32x4*)(baseb + off + bj * HALF);
;                     const f32x4 b0 = {bf_lo(bw.x), bf_hi(bw.x), bf_lo(bw.y), bf_hi(bw.y)}, b1 = {bf_lo(bw.z), bf_hi(bw.z), bf_lo(bw.w), bf_hi(bw.w)};
;                     const u32x4 pw = *(const GAS u32x4*)(pp + off + bj * HALF);
;                     const f32x4 p0 = {bf_lo(pw.x), bf_hi(pw.x), bf_lo(pw.y), bf_hi(pw.y)}, p1 = {bf_lo(pw.z), bf_hi(pw.z), bf_lo(pw.w), bf_hi(pw.w)};
;                     const f32x4 z0 = acc[ai][bj][m][0] + bv[bj][0], z1 = acc[ai][bj][m][1] + bv[bj][1]; f32x4 g0, g1;
; #pragma unroll
;                     for (int i = 0; i < 4; ++i) { g0[i] = __builtin_amdgcn_rcpf(1.f + __expf(-z0[i])); g1[i] = __builtin_amdgcn_rcpf(1.f + __expf(-z1[i])); }
;                     const f32x4 o0 = b0 + g0 * p0, o1 = b1 + g1 * p1;
;                     if (out) { *(GAS f32x4*)(out + off + bj * HALF) = o0; *(GAS f32x4*)(out + off + bj * HALF + 4) = o1; }
;                     if (xb) { q[ai][m] += (o0[0] * o0[0] + o0[1] * o0[1]) + (o0[2] * o0[2] + o0[3] * o0[3]) + (o1[0] * o1[0] + o1[1] * o1[1]) + (o1[2] * o1[2] + o1[3] * o1[3]);
;                         u32x4 w; w.x = cvt_pk_bf16(o0[0], o0[1]); w.y = cvt_pk_bf16(o0[2], o0[3]); w.z = cvt_pk_bf16(o1[0], o1[1]); w.w = cvt_pk_bf16(o1[2], o1[3]); *(GAS u32x4*)(xb + off + bj * HALF) = w; } } }
	v_lshlrev_b64 v[160:161], 1, v[160:161]
	global_store_dwordx4 v[162:163], v[170:173], off
	s_nop 3
	v_lshl_add_u64 v[182:183], s[34:35], 0, v[160:161]
	v_add_f32_e32 v103, v103, v31
	v_add_f32_e32 v99, v99, v27
	v_mul_f32_e32 v100, 0xbfb8aa3b, v100
	v_mul_f32_e32 v96, 0xbfb8aa3b, v96
	v_mul_f32_e32 v101, 0xbfb8aa3b, v101
	v_mul_f32_e32 v97, 0xbfb8aa3b, v97
	v_mul_f32_e32 v102, 0xbfb8aa3b, v102
	v_mul_f32_e32 v98, 0xbfb8aa3b, v98
	v_mul_f32_e32 v103, 0xbfb8aa3b, v103
	v_mul_f32_e32 v99, 0xbfb8aa3b, v99
	v_exp_f32_e32 v100, v100
	v_exp_f32_e32 v96, v96
	v_exp_f32_e32 v101, v101
	v_exp_f32_e32 v97, v97
	v_exp_f32_e32 v102, v102
	v_exp_f32_e32 v98, v98
	v_exp_f32_e32 v103, v103
	v_exp_f32_e32 v99, v99
	v_add_f32_e32 v100, 1.0, v100
	v_add_f32_e32 v101, 1.0, v101
	v_add_f32_e32 v102, 1.0, v102
	v_add_f32_e32 v103, 1.0, v103
	v_add_f32_e32 v92, v92, v44
	v_add_f32_e32 v88, v88, v40
	v_add_f32_e32 v93, v93, v45
	v_add_f32_e32 v89, v89, v41
	v_add_f32_e32 v94, v94, v46
	v_add_f32_e32 v90, v90, v42
	v_add_f32_e32 v95, v95, v47
	v_add_f32_e32 v91, v91, v43
	v_mul_f32_e32 v92, 0xbfb8aa3b, v92
	v_mul_f32_e32 v88, 0xbfb8aa3b, v88
	v_mul_f32_e32 v93, 0xbfb8aa3b, v93
	v_mul_f32_e32 v89, 0xbfb8aa3b, v89
	v_mul_f32_e32 v94, 0xbfb8aa3b, v94
	v_mul_f32_e32 v90, 0xbfb8aa3b, v90
	v_mul_f32_e32 v95, 0xbfb8aa3b, v95
	v_mul_f32_e32 v91, 0xbfb8aa3b, v91
	v_exp_f32_e32 v92, v92
	v_exp_f32_e32 v88, v88
	v_exp_f32_e32 v93, v93
	v_exp_f32_e32 v89, v89
	v_exp_f32_e32 v94, v94
	v_exp_f32_e32 v90, v90
	v_exp_f32_e32 v95, v95
	v_exp_f32_e32 v91, v91
	v_add_f32_e32 v92, 1.0, v92
	v_add_f32_e32 v88, 1.0, v88
	v_add_f32_e32 v93, 1.0, v93
	v_add_f32_e32 v89, 1.0, v89
	v_add_f32_e32 v84, v84, v28
	v_add_f32_e32 v80, v80, v24
	v_add_f32_e32 v85, v85, v29
	v_add_f32_e32 v81, v81, v25
	v_add_f32_e32 v86, v86, v30
	v_add_f32_e32 v82, v82, v26
	v_add_f32_e32 v87, v87, v31
	v_add_f32_e32 v83, v83, v27
	v_mul_f32_e32 v84, 0xbfb8aa3b, v84
	v_mul_f32_e32 v80, 0xbfb8aa3b, v80
	v_mul_f32_e32 v85, 0xbfb8aa3b, v85
	v_mul_f32_e32 v81, 0xbfb8aa3b, v81
	v_mul_f32_e32 v86, 0xbfb8aa3b, v86
	v_mul_f32_e32 v82, 0xbfb8aa3b, v82
	v_mul_f32_e32 v87, 0xbfb8aa3b, v87
	v_mul_f32_e32 v83, 0xbfb8aa3b, v83
	s_waitcnt vmcnt(7)
	v_mov_b32_e32 v174, v192
	v_mov_b32_e32 v175, v193
	v_mov_b32_e32 v176, v194
	v_mov_b32_e32 v177, v195
	v_mov_b32_e32 v178, v196
	v_mov_b32_e32 v179, v197
	v_mov_b32_e32 v180, v198
	v_mov_b32_e32 v181, v199
	s_add_u32 vcc_lo, s34, 0x30000
	s_addc_u32 vcc_hi, s35, 0
	global_load_dwordx4 v[192:195], v156, vcc
	s_add_u32 vcc_lo, s30, 0x30000
	s_addc_u32 vcc_hi, s31, 0
	global_load_dwordx4 v[196:199], v156, vcc
	v_lshlrev_b32_e32 v118, 16, v174
	v_and_b32_e32 v119, 0xffff0000, v174
	v_lshlrev_b32_e32 v170, 16, v175
	v_and_b32_e32 v171, 0xffff0000, v175
	v_lshlrev_b32_e32 v172, 16, v176
	v_and_b32_e32 v173, 0xffff0000, v176
	v_lshlrev_b32_e32 v174, 16, v177
	v_and_b32_e32 v175, 0xffff0000, v177
	v_lshlrev_b32_e32 v176, 16, v178
	v_and_b32_e32 v177, 0xffff0000, v178
	v_lshlrev_b32_e32 v178, 16, v179
	v_and_b32_e32 v179, 0xffff0000, v179
	v_lshlrev_b32_e32 v190, 16, v180
	v_and_b32_e32 v191, 0xffff0000, v180
	v_lshlrev_b32_e32 v180, 16, v181
	v_and_b32_e32 v181, 0xffff0000, v181
	v_pk_fma_f32 v[116:117], v[116:117], v[178:179], v[170:171]
	v_pk_fma_f32 v[118:119], v[112:113], v[176:177], v[118:119]
	v_pk_fma_f32 v[112:113], v[188:189], v[180:181], v[174:175]
	v_pk_fma_f32 v[114:115], v[114:115], v[190:191], v[172:173]
	v_cvt_pk_bf16_f32 v170, v118, v119
	v_cvt_pk_bf16_f32 v171, v116, v117
	v_add_f32_e32 v178, 1.0, v110
	v_cvt_pk_bf16_f32 v172, v114, v115
	v_cvt_pk_bf16_f32 v173, v112, v113
	global_store_dwordx4 v[162:163], v[170:173], off offset:256
	s_nop 3
	v_lshl_add_u64 v[162:163], s[30:31], 0, v[160:161]
	v_add_f32_e32 v179, 1.0, v106
	v_add_f32_e32 v180, 1.0, v111
	v_add_f32_e32 v181, 1.0, v107
	v_rcp_f32_e32 v106, v108
	v_rcp_f32_e32 v110, v104
	v_rcp_f32_e32 v107, v109
	v_rcp_f32_e32 v111, v105
	v_rcp_f32_e32 v104, v178
	v_rcp_f32_e32 v178, v179
	v_rcp_f32_e32 v105, v180
	v_rcp_f32_e32 v179, v181
	v_exp_f32_e32 v84, v84
	v_exp_f32_e32 v80, v80
	v_exp_f32_e32 v85, v85
	v_exp_f32_e32 v81, v81
	v_exp_f32_e32 v86, v86
	v_exp_f32_e32 v82, v82
	v_exp_f32_e32 v87, v87
	v_exp_f32_e32 v83, v83
	v_add_f32_e32 v84, 1.0, v84
	v_add_f32_e32 v85, 1.0, v85
	v_add_f32_e32 v86, 1.0, v86
	v_add_f32_e32 v186, 1.0, v82
	v_add_f32_e32 v87, 1.0, v87
	v_add_f32_e32 v187, 1.0, v83
	v_add_f32_e32 v76, v76, v44
	v_add_f32_e32 v72, v72, v40
	v_add_f32_e32 v77, v77, v45
	v_add_f32_e32 v73, v73, v41
	v_add_f32_e32 v78, v78, v46
	v_add_f32_e32 v74, v74, v42
	v_add_f32_e32 v79, v79, v47
	v_add_f32_e32 v75, v75, v43
	v_mul_f32_e32 v76, 0xbfb8aa3b, v76
	v_mul_f32_e32 v72, 0xbfb8aa3b, v72
	v_mul_f32_e32 v77, 0xbfb8aa3b, v77
	v_mul_f32_e32 v73, 0xbfb8aa3b, v73
	v_mul_f32_e32 v78, 0xbfb8aa3b, v78
	v_mul_f32_e32 v74, 0xbfb8aa3b, v74
	v_mul_f32_e32 v79, 0xbfb8aa3b, v79
	v_mul_f32_e32 v75, 0xbfb8aa3b, v75
	v_exp_f32_e32 v76, v76
	v_exp_f32_e32 v72, v72
	v_exp_f32_e32 v77, v77
	v_exp_f32_e32 v73, v73
	v_exp_f32_e32 v78, v78
	v_exp_f32_e32 v74, v74
	v_exp_f32_e32 v79, v79
	v_exp_f32_e32 v75, v75
	v_add_f32_e32 v76, 1.0, v76
	v_add_f32_e32 v72, 1.0, v72
	v_add_f32_e32 v77, 1.0, v77
	v_add_f32_e32 v73, 1.0, v73
	v_add_f32_e32 v68, v68, v28
	v_add_f32_e32 v64, v64, v24
	v_add_f32_e32 v69, v69, v29
	v_add_f32_e32 v65, v65, v25
	v_add_f32_e32 v70, v70, v30
	v_add_f32_e32 v66, v66, v26
	v_add_f32_e32 v71, v71, v31
	v_add_f32_e32 v67, v67, v27
	v_mul_f32_e32 v68, 0xbfb8aa3b, v68
	v_mul_f32_e32 v64, 0xbfb8aa3b, v64
	v_mul_f32_e32 v69, 0xbfb8aa3b, v69
	v_mul_f32_e32 v65, 0xbfb8aa3b, v65
	v_mul_f32_e32 v70, 0xbfb8aa3b, v70
	v_mul_f32_e32 v66, 0xbfb8aa3b, v66
	v_mul_f32_e32 v71, 0xbfb8aa3b, v71
	v_mul_f32_e32 v67, 0xbfb8aa3b, v67
	v_exp_f32_e32 v68, v68
	v_exp_f32_e32 v64, v64
	v_exp_f32_e32 v69, v69
	v_exp_f32_e32 v65, v65
	v_exp_f32_e32 v70, v70
	v_exp_f32_e32 v66, v66
	v_exp_f32_e32 v71, v71
	v_exp_f32_e32 v67, v67
	v_add_f32_e32 v68, 1.0, v68
	s_waitcnt vmcnt(7)
; #define GAS __attribute__((address_space(1)))
; __device__ __forceinline__ unsigned cvt_pk_bf16(float lo, float hi) { unsigned r; asm volatile("v_cvt_pk_bf16_f32 %0, %1, %2" : "=v"(r) : "v"(lo), "v"(hi)); return r; }
; __device__ __forceinline__ float bf_lo(unsigned w) { return __uint_as_float(w << 16); }
; __device__ __forceinline__ float bf_hi(unsigned w) { return __uint_as_float(w & 0xffff0000u); }
;     __device__ __forceinline__ void operator()(const f32x4 (&acc)[2][2][4][2], const Unit& u, int wr, int wc, int fr, int fq) const {
;     ...
;             for (int m = 0; m < 4; ++m) { const size_t off = (size_t)(row0 + ai * HALF + m * 16) * DM + col0; q[ai][m] = 0.f;
; #pragma unroll
;                 for (int bj = 0; bj < 2; ++bj) { const u32x4 bw = *(const GAS u32x4*)(baseb + off + bj * HALF);
;                     const f32x4 b0 = {bf_lo(bw.x), bf_hi(bw.x), bf_lo(bw.y), bf_hi(bw.y)}, b1 = {bf_lo(bw.z), bf_hi(bw.z), bf_lo(bw.w), bf_hi(bw.w)};
;                     const u32x4 pw = *(const GAS u32x4*)(pp + off + bj * HALF);
;                     const f32x4 p0 = {bf_lo(pw.x), bf_hi(pw.x), bf_lo(pw.y), bf_hi(pw.y)}, p1 = {bf_lo(pw.z), bf_hi(pw.z), bf_lo(pw.w), bf_hi(pw.w)};
;                     const f32x4 z0 = acc[ai][bj][m][0] + bv[bj][0], z1 = acc[ai][bj][m][1] + bv[bj][1]; f32x4 g0, g1;
; #pragma unroll
;                     for (int i = 0; i < 4; ++i) { g0[i] = __builtin_amdgcn_rcpf(1.f + __expf(-z0[i])); g1[i] = __builtin_amdgcn_rcpf(1.f + __expf(-z1[i])); }
;                     const f32x4 o0 = b0 + g0 * p0, o1 = b1 + g1 * p1;
;                     if (out) { *(GAS f32x4*)(out + off + bj * HALF) = o0; *(GAS f32x4*)(out + off + bj * HALF + 4) = o1; }
;                     if (xb) { q[ai][m] += (o0[0] * o0[0] + o0[1] * o0[1]) + (o0[2] * o0[2] + o0[3] * o0[3]) + (o1[0] * o1[0] + o1[1] * o1[1]) + (o1[2] * o1[2] + o1[3] * o1[3]);
;                         u32x4 w; w.x = cvt_pk_bf16(o0[0], o0[1]); w.y = cvt_pk_bf16(o0[2], o0[3]); w.z = cvt_pk_bf16(o1[0], o1[1]); w.w = cvt_pk_bf16(o1[2], o1[3]); *(GAS u32x4*)(xb + off + bj * HALF) = w; } } }
	v_mov_b32_e32 v170, v200
	v_mov_b32_e32 v171, v201
	v_mov_b32_e32 v172, v202
	v_mov_b32_e32 v173, v203
	v_mov_b32_e32 v174, v204
	v_mov_b32_e32 v175, v205
	v_mov_b32_e32 v176, v206
	v_mov_b32_e32 v177, v207
	s_add_u32 vcc_lo, s34, 0x30000
	s_addc_u32 vcc_hi, s35, 0
	global_load_dwordx4 v[200:203], v156, vcc offset:256
	s_add_u32 vcc_lo, s30, 0x30000
	s_addc_u32 vcc_hi, s31, 0
	global_load_dwordx4 v[204:207], v156, vcc offset:256
	v_lshlrev_b32_e32 v108, 16, v170
	v_and_b32_e32 v109, 0xffff0000, v170
	v_lshlrev_b32_e32 v170, 16, v171
	v_and_b32_e32 v171, 0xffff0000, v171
	v_lshlrev_b32_e32 v180, 16, v172
	v_and_b32_e32 v181, 0xffff0000, v172
	v_lshlrev_b32_e32 v172, 16, v173
	v_and_b32_e32 v173, 0xffff0000, v173
	v_lshlrev_b32_e32 v188, 16, v174
	v_and_b32_e32 v189, 0xffff0000, v174
	v_lshlrev_b32_e32 v174, 16, v175
	v_and_b32_e32 v175, 0xffff0000, v175
	v_lshlrev_b32_e32 v190, 16, v176
	v_and_b32_e32 v191, 0xffff0000, v176
	v_lshlrev_b32_e32 v176, 16, v177
	v_and_b32_e32 v177, 0xffff0000, v177
	v_pk_fma_f32 v[104:105], v[104:105], v[174:175], v[170:171]
	v_pk_fma_f32 v[108:109], v[106:107], v[188:189], v[108:109]
	v_pk_fma_f32 v[106:107], v[178:179], v[176:177], v[172:173]
	v_pk_fma_f32 v[110:111], v[110:111], v[190:191], v[180:181]
	v_cvt_pk_bf16_f32 v170, v108, v109
	v_cvt_pk_bf16_f32 v171, v104, v105
	v_add_f32_e32 v69, 1.0, v69
	v_cvt_pk_bf16_f32 v172, v110, v111
	v_cvt_pk_bf16_f32 v173, v106, v107
	v_or_b32_e32 v162, 48, v154
	v_ashrrev_i32_e32 v163, 31, v162
	v_lshlrev_b64 v[162:163], 11, v[162:163]
	v_lshl_add_u64 v[158:159], v[162:163], 0, v[158:159]
	v_lshl_add_u64 v[182:183], s[96:97], 0, v[160:161]
	v_add_f32_e32 v160, 1.0, v96
	v_add_f32_e32 v161, 1.0, v97
	v_add_f32_e32 v162, 1.0, v98
	v_add_f32_e32 v163, 1.0, v99
	v_rcp_f32_e32 v96, v100
	v_rcp_f32_e32 v98, v160
	v_rcp_f32_e32 v97, v101
	v_rcp_f32_e32 v99, v161
	v_rcp_f32_e32 v100, v102
	v_rcp_f32_e32 v160, v162
	v_rcp_f32_e32 v101, v103
	v_rcp_f32_e32 v161, v163
	v_lshlrev_b64 v[158:159], 1, v[158:159]
	global_store_dwordx4 v[182:183], v[170:173], off
	s_nop 3
	v_lshl_add_u64 v[188:189], s[34:35], 0, v[158:159]
	v_add_f32_e32 v70, 1.0, v70
	v_add_f32_e32 v71, 1.0, v71
	v_add_f32_e32 v60, v60, v44
	v_add_f32_e32 v56, v56, v40
	v_add_f32_e32 v61, v61, v45
	v_add_f32_e32 v57, v57, v41
	v_add_f32_e32 v62, v62, v46
	v_add_f32_e32 v58, v58, v42
	v_add_f32_e32 v63, v63, v47
	v_add_f32_e32 v59, v59, v43
	v_mul_f32_e32 v60, 0xbfb8aa3b, v60
	v_mul_f32_e32 v56, 0xbfb8aa3b, v56
	v_mul_f32_e32 v61, 0xbfb8aa3b, v61
	v_mul_f32_e32 v57, 0xbfb8aa3b, v57
	v_mul_f32_e32 v62, 0xbfb8aa3b, v62
	v_mul_f32_e32 v58, 0xbfb8aa3b, v58
	v_mul_f32_e32 v63, 0xbfb8aa3b, v63
	v_mul_f32_e32 v59, 0xbfb8aa3b, v59
	v_exp_f32_e32 v60, v60
	v_exp_f32_e32 v56, v56
	v_exp_f32_e32 v61, v61
	v_exp_f32_e32 v57, v57
	v_exp_f32_e32 v62, v62
	v_exp_f32_e32 v58, v58
	v_exp_f32_e32 v63, v63
	v_exp_f32_e32 v59, v59
	v_add_f32_e32 v60, 1.0, v60
	v_add_f32_e32 v56, 1.0, v56
	v_add_f32_e32 v61, 1.0, v61
	v_add_f32_e32 v57, 1.0, v57
	v_add_f32_e32 v52, v52, v28
	v_add_f32_e32 v48, v48, v24
	v_add_f32_e32 v53, v53, v29
	v_add_f32_e32 v49, v49, v25
	v_add_f32_e32 v54, v54, v30
	v_add_f32_e32 v50, v50, v26
	v_add_f32_e32 v55, v55, v31
	v_add_f32_e32 v51, v51, v27
	v_mul_f32_e32 v52, 0xbfb8aa3b, v52
	v_mul_f32_e32 v48, 0xbfb8aa3b, v48
	v_mul_f32_e32 v53, 0xbfb8aa3b, v53
	v_mul_f32_e32 v49, 0xbfb8aa3b, v49
	v_mul_f32_e32 v54, 0xbfb8aa3b, v54
	v_mul_f32_e32 v50, 0xbfb8aa3b, v50
	v_mul_f32_e32 v55, 0xbfb8aa3b, v55
	v_mul_f32_e32 v51, 0xbfb8aa3b, v51
	v_exp_f32_e32 v52, v52
	v_exp_f32_e32 v48, v48
	v_exp_f32_e32 v53, v53
	v_exp_f32_e32 v49, v49
	v_exp_f32_e32 v54, v54
	v_exp_f32_e32 v50, v50
	v_exp_f32_e32 v55, v55
	v_exp_f32_e32 v51, v51
	v_add_f32_e32 v52, 1.0, v52
	v_add_f32_e32 v53, 1.0, v53
	v_add_f32_e32 v54, 1.0, v54
	v_add_f32_e32 v55, 1.0, v55
	s_waitcnt vmcnt(7)
	v_mov_b32_e32 v174, v208
	v_mov_b32_e32 v175, v209
	v_mov_b32_e32 v176, v210
	v_mov_b32_e32 v177, v211
	v_mov_b32_e32 v178, v212
	v_mov_b32_e32 v179, v213
	v_mov_b32_e32 v180, v214
	v_mov_b32_e32 v181, v215
	s_add_u32 vcc_lo, s34, 0x80000
	s_addc_u32 vcc_hi, s35, 0
	global_load_dwordx4 v[208:211], v156, vcc
	s_add_u32 vcc_lo, s30, 0x80000
	s_addc_u32 vcc_hi, s31, 0
	global_load_dwordx4 v[212:215], v156, vcc
	v_lshlrev_b32_e32 v102, 16, v174
	v_and_b32_e32 v103, 0xffff0000, v174
	v_lshlrev_b32_e32 v162, 16, v175
	v_and_b32_e32 v163, 0xffff0000, v175
	v_lshlrev_b32_e32 v170, 16, v176
	v_and_b32_e32 v171, 0xffff0000, v176
	v_lshlrev_b32_e32 v172, 16, v177
	v_and_b32_e32 v173, 0xffff0000, v177
	v_lshlrev_b32_e32 v174, 16, v178
	v_and_b32_e32 v175, 0xffff0000, v178
	v_lshlrev_b32_e32 v176, 16, v179
	v_and_b32_e32 v177, 0xffff0000, v179
	v_lshlrev_b32_e32 v178, 16, v180
	v_and_b32_e32 v179, 0xffff0000, v180
	v_lshlrev_b32_e32 v180, 16, v181
	v_and_b32_e32 v181, 0xffff0000, v181
	v_pk_fma_f32 v[100:101], v[100:101], v[176:177], v[162:163]
	v_pk_fma_f32 v[102:103], v[96:97], v[174:175], v[102:103]
	v_pk_fma_f32 v[96:97], v[160:161], v[180:181], v[172:173]
	v_pk_fma_f32 v[98:99], v[98:99], v[178:179], v[170:171]
	v_cvt_pk_bf16_f32 v160, v102, v103
	v_cvt_pk_bf16_f32 v161, v100, v101
	v_lshl_add_u64 v[178:179], s[30:31], 0, v[158:159]
	v_cvt_pk_bf16_f32 v162, v98, v99
	v_cvt_pk_bf16_f32 v163, v96, v97
	global_store_dwordx4 v[182:183], v[160:163], off offset:256
	s_nop 3
	v_add_f32_e32 v174, 1.0, v94
	v_add_f32_e32 v175, 1.0, v90
	v_add_f32_e32 v176, 1.0, v95
	v_add_f32_e32 v177, 1.0, v91
	v_rcp_f32_e32 v90, v92
	v_rcp_f32_e32 v94, v88
	v_rcp_f32_e32 v91, v93
	v_rcp_f32_e32 v95, v89
	v_rcp_f32_e32 v88, v174
	v_rcp_f32_e32 v174, v175
	v_rcp_f32_e32 v89, v176
	v_rcp_f32_e32 v175, v177
; #define GAS __attribute__((address_space(1)))
; __device__ __forceinline__ unsigned cvt_pk_bf16(float lo, float hi) { unsigned r; asm volatile("v_cvt_pk_bf16_f32 %0, %1, %2" : "=v"(r) : "v"(lo), "v"(hi)); return r; }
; __device__ __forceinline__ float bf_lo(unsigned w) { return __uint_as_float(w << 16); }
; __device__ __forceinline__ float bf_hi(unsigned w) { return __uint_as_float(w & 0xffff0000u); }
;     __device__ __forceinline__ void operator()(const f32x4 (&acc)[2][2][4][2], const Unit& u, int wr, int wc, int fr, int fq) const {
;     ...
;             for (int m = 0; m < 4; ++m) { const size_t off = (size_t)(row0 + ai * HALF + m * 16) * DM + col0; q[ai][m] = 0.f;
; #pragma unroll
;                 for (int bj = 0; bj < 2; ++bj) { const u32x4 bw = *(const GAS u32x4*)(baseb + off + bj * HALF);
;                     const f32x4 b0 = {bf_lo(bw.x), bf_hi(bw.x), bf_lo(bw.y), bf_hi(bw.y)}, b1 = {bf_lo(bw.z), bf_hi(bw.z), bf_lo(bw.w), bf_hi(bw.w)};
;                     const u32x4 pw = *(const GAS u32x4*)(pp + off + bj * HALF);
;                     const f32x4 p0 = {bf_lo(pw.x), bf_hi(pw.x), bf_lo(pw.y), bf_hi(pw.y)}, p1 = {bf_lo(pw.z), bf_hi(pw.z), bf_lo(pw.w), bf_hi(pw.w)};
;                     const f32x4 z0 = acc[ai][bj][m][0] + bv[bj][0], z1 = acc[ai][bj][m][1] + bv[bj][1]; f32x4 g0, g1;
; #pragma unroll
;                     for (int i = 0; i < 4; ++i) { g0[i] = __builtin_amdgcn_rcpf(1.f + __expf(-z0[i])); g1[i] = __builtin_amdgcn_rcpf(1.f + __expf(-z1[i])); }
;                     const f32x4 o0 = b0 + g0 * p0, o1 = b1 + g1 * p1;
;                     if (out) { *(GAS f32x4*)(out + off + bj * HALF) = o0; *(GAS f32x4*)(out + off + bj * HALF + 4) = o1; }
;                     if (xb) { q[ai][m] += (o0[0] * o0[0] + o0[1] * o0[1]) + (o0[2] * o0[2] + o0[3] * o0[3]) + (o1[0] * o1[0] + o1[1] * o1[1]) + (o1[2] * o1[2] + o1[3] * o1[3]);
;                         u32x4 w; w.x = cvt_pk_bf16(o0[0], o0[1]); w.y = cvt_pk_bf16(o0[2], o0[3]); w.z = cvt_pk_bf16(o1[0], o1[1]); w.w = cvt_pk_bf16(o1[2], o1[3]); *(GAS u32x4*)(xb + off + bj * HALF) = w; } } }
	v_lshl_add_u64 v[158:159], s[96:97], 0, v[158:159]
	v_add_f32_e32 v36, v36, v44
	v_add_f32_e32 v32, v32, v40
	v_add_f32_e32 v37, v37, v45
	v_add_f32_e32 v33, v33, v41
	v_add_f32_e32 v38, v38, v46
	v_add_f32_e32 v34, v34, v42
	v_add_f32_e32 v39, v39, v47
	v_add_f32_e32 v35, v35, v43
	v_mul_f32_e32 v36, 0xbfb8aa3b, v36
	v_mul_f32_e32 v32, 0xbfb8aa3b, v32
	v_mul_f32_e32 v37, 0xbfb8aa3b, v37
	v_mul_f32_e32 v33, 0xbfb8aa3b, v33
	v_mul_f32_e32 v38, 0xbfb8aa3b, v38
	v_mul_f32_e32 v34, 0xbfb8aa3b, v34
	v_mul_f32_e32 v39, 0xbfb8aa3b, v39
	v_mul_f32_e32 v35, 0xbfb8aa3b, v35
	v_exp_f32_e32 v36, v36
	v_exp_f32_e32 v32, v32
	v_exp_f32_e32 v37, v37
	v_exp_f32_e32 v33, v33
	v_exp_f32_e32 v38, v38
	v_exp_f32_e32 v34, v34
	v_exp_f32_e32 v39, v39
	v_exp_f32_e32 v35, v35
	v_add_f32_e32 v36, 1.0, v36
	v_add_f32_e32 v32, 1.0, v32
	v_add_f32_e32 v37, 1.0, v37
	v_add_f32_e32 v33, 1.0, v33
	v_add_f32_e32 v20, v20, v28
	v_add_f32_e32 v16, v16, v24
	v_add_f32_e32 v21, v21, v29
	v_add_f32_e32 v17, v17, v25
	v_add_f32_e32 v22, v22, v30
	v_add_f32_e32 v18, v18, v26
	v_add_f32_e32 v23, v23, v31
	v_add_f32_e32 v19, v19, v27
	v_mul_f32_e32 v20, 0xbfb8aa3b, v20
	v_mul_f32_e32 v16, 0xbfb8aa3b, v16
	v_mul_f32_e32 v21, 0xbfb8aa3b, v21
	v_mul_f32_e32 v17, 0xbfb8aa3b, v17
	v_mul_f32_e32 v22, 0xbfb8aa3b, v22
	v_mul_f32_e32 v18, 0xbfb8aa3b, v18
	v_mul_f32_e32 v23, 0xbfb8aa3b, v23
	v_mul_f32_e32 v19, 0xbfb8aa3b, v19
	v_exp_f32_e32 v20, v20
	v_exp_f32_e32 v16, v16
	v_exp_f32_e32 v21, v21
	v_exp_f32_e32 v17, v17
	v_exp_f32_e32 v22, v22
	v_exp_f32_e32 v18, v18
	v_exp_f32_e32 v23, v23
	v_exp_f32_e32 v19, v19
	v_add_f32_e32 v20, 1.0, v20
	v_add_f32_e32 v21, 1.0, v21
	v_add_f32_e32 v22, 1.0, v22
	v_add_f32_e32 v23, 1.0, v23
	v_add_f32_e32 v12, v12, v44
	v_add_f32_e32 v8, v8, v40
	v_add_f32_e32 v13, v13, v45
	v_add_f32_e32 v9, v9, v41
	v_add_f32_e32 v14, v14, v46
	v_add_f32_e32 v10, v10, v42
	v_add_f32_e32 v15, v15, v47
	v_add_f32_e32 v11, v11, v43
	v_mul_f32_e32 v12, 0xbfb8aa3b, v12
	s_waitcnt vmcnt(7)
	v_mov_b32_e32 v160, v192
	v_mov_b32_e32 v161, v193
	v_mov_b32_e32 v162, v194
	v_mov_b32_e32 v163, v195
	v_mov_b32_e32 v170, v196
	v_mov_b32_e32 v171, v197
	v_mov_b32_e32 v172, v198
	v_mov_b32_e32 v173, v199
	s_add_u32 vcc_lo, s34, 0x80000
	s_addc_u32 vcc_hi, s35, 0
	global_load_dwordx4 v[192:195], v156, vcc offset:256
	s_add_u32 vcc_lo, s30, 0x80000
	s_addc_u32 vcc_hi, s31, 0
	global_load_dwordx4 v[196:199], v156, vcc offset:256
	v_lshlrev_b32_e32 v92, 16, v160
	v_and_b32_e32 v93, 0xffff0000, v160
	v_lshlrev_b32_e32 v160, 16, v161
	v_and_b32_e32 v161, 0xffff0000, v161
	v_lshlrev_b32_e32 v176, 16, v162
	v_and_b32_e32 v177, 0xffff0000, v162
	v_lshlrev_b32_e32 v162, 16, v163
	v_and_b32_e32 v163, 0xffff0000, v163
	v_lshlrev_b32_e32 v180, 16, v170
	v_and_b32_e32 v181, 0xffff0000, v170
	v_lshlrev_b32_e32 v170, 16, v171
	v_and_b32_e32 v171, 0xffff0000, v171
	v_lshlrev_b32_e32 v182, 16, v172
	v_and_b32_e32 v183, 0xffff0000, v172
	v_lshlrev_b32_e32 v172, 16, v173
	v_and_b32_e32 v173, 0xffff0000, v173
	v_pk_fma_f32 v[88:89], v[88:89], v[170:171], v[160:161]
	v_pk_fma_f32 v[92:93], v[90:91], v[180:181], v[92:93]
	v_pk_fma_f32 v[90:91], v[174:175], v[172:173], v[162:163]
	v_pk_fma_f32 v[94:95], v[94:95], v[182:183], v[176:177]
	v_cvt_pk_bf16_f32 v170, v92, v93
	v_cvt_pk_bf16_f32 v171, v88, v89
	v_add_f32_e32 v182, 1.0, v80
	v_cvt_pk_bf16_f32 v172, v94, v95
	v_cvt_pk_bf16_f32 v173, v90, v91
	s_nop 0
	v_add_f32_e32 v183, 1.0, v81
	v_rcp_f32_e32 v80, v84
	v_rcp_f32_e32 v82, v182
	v_rcp_f32_e32 v81, v85
	v_rcp_f32_e32 v83, v183
	v_rcp_f32_e32 v84, v86
	v_rcp_f32_e32 v182, v186
	v_rcp_f32_e32 v85, v87
	v_rcp_f32_e32 v183, v187
	v_lshl_add_u64 v[160:161], v[156:157], 0, s[40:41]
	global_store_dwordx4 v[158:159], v[170:173], off
	s_nop 3
	v_lshl_add_u64 v[162:163], s[34:35], 0, v[160:161]
	v_add_f32_e32 v186, 1.0, v50
	v_add_f32_e32 v187, 1.0, v51
	s_mov_b64 s[40:41], 0xa0000
	v_mul_f32_e32 v8, 0xbfb8aa3b, v8
	v_mul_f32_e32 v13, 0xbfb8aa3b, v13
	v_mul_f32_e32 v9, 0xbfb8aa3b, v9
	v_mul_f32_e32 v14, 0xbfb8aa3b, v14
	v_mul_f32_e32 v10, 0xbfb8aa3b, v10
	v_mul_f32_e32 v15, 0xbfb8aa3b, v15
	v_mul_f32_e32 v11, 0xbfb8aa3b, v11
	v_exp_f32_e32 v12, v12
	v_exp_f32_e32 v8, v8
	v_exp_f32_e32 v13, v13
	v_exp_f32_e32 v9, v9
	v_exp_f32_e32 v14, v14
	v_exp_f32_e32 v10, v10
	v_exp_f32_e32 v15, v15
	v_exp_f32_e32 v11, v11
	v_add_f32_e32 v12, 1.0, v12
	v_add_f32_e32 v8, 1.0, v8
	v_add_f32_e32 v13, 1.0, v13
	v_add_f32_e32 v9, 1.0, v9
	v_add_f32_e32 v40, 1.0, v14
	v_add_f32_e32 v41, 1.0, v10
	v_add_f32_e32 v42, 1.0, v15
	v_add_f32_e32 v43, 1.0, v11
	v_rcp_f32_e32 v10, v12
	v_rcp_f32_e32 v14, v8
	v_rcp_f32_e32 v11, v13
	v_rcp_f32_e32 v15, v9
	v_rcp_f32_e32 v8, v40
	v_rcp_f32_e32 v40, v41
	v_rcp_f32_e32 v9, v42
	v_rcp_f32_e32 v41, v43
	v_add_f32_e32 v4, v4, v28
	v_add_f32_e32 v0, v0, v24
	v_add_f32_e32 v2, v2, v26
	v_add_f32_e32 v3, v3, v27
	v_add_f32_e32 v5, v5, v29
	v_add_f32_e32 v1, v1, v25
	v_mul_f32_e32 v4, 0xbfb8aa3b, v4
	v_mul_f32_e32 v0, 0xbfb8aa3b, v0
	v_mul_f32_e32 v2, 0xbfb8aa3b, v2
	v_mul_f32_e32 v3, 0xbfb8aa3b, v3
	v_mul_f32_e32 v5, 0xbfb8aa3b, v5
	v_mul_f32_e32 v1, 0xbfb8aa3b, v1
	v_exp_f32_e32 v4, v4
	v_exp_f32_e32 v0, v0
	v_exp_f32_e32 v2, v2
	v_exp_f32_e32 v3, v3
	v_exp_f32_e32 v5, v5
	v_exp_f32_e32 v1, v1
	v_add_f32_e32 v4, 1.0, v4
	v_add_f32_e32 v24, 1.0, v0
	v_add_f32_e32 v26, 1.0, v2
	v_add_f32_e32 v27, 1.0, v3
	v_mul_f32_e32 v2, v139, v139
	v_mul_f32_e32 v3, v137, v137
	v_add_f32_e32 v5, 1.0, v5
	v_add_f32_e32 v25, 1.0, v1
	v_rcp_f32_e32 v0, v4
	v_rcp_f32_e32 v4, v24
	v_mul_f32_e32 v24, v143, v143
	v_fmac_f32_e32 v2, v138, v138
	v_fmac_f32_e32 v3, v136, v136
	v_rcp_f32_e32 v1, v5
	s_waitcnt vmcnt(7)
; #define GAS __attribute__((address_space(1)))
; __device__ __forceinline__ unsigned cvt_pk_bf16(float lo, float hi) { unsigned r; asm volatile("v_cvt_pk_bf16_f32 %0, %1, %2" : "=v"(r) : "v"(lo), "v"(hi)); return r; }
; __device__ __forceinline__ float bf_lo(unsigned w) { return __uint_as_float(w << 16); }
; __device__ __forceinline__ float bf_hi(unsigned w) { return __uint_as_float(w & 0xffff0000u); }
;     __device__ __forceinline__ void operator()(const f32x4 (&acc)[2][2][4][2], const Unit& u, int wr, int wc, int fr, int fq) const {
;     ...
;             for (int m = 0; m < 4; ++m) { const size_t off = (size_t)(row0 + ai * HALF + m * 16) * DM + col0; q[ai][m] = 0.f;
; #pragma unroll
;                 for (int bj = 0; bj < 2; ++bj) { const u32x4 bw = *(const GAS u32x4*)(baseb + off + bj * HALF);
;                     const f32x4 b0 = {bf_lo(bw.x), bf_hi(bw.x), bf_lo(bw.y), bf_hi(bw.y)}, b1 = {bf_lo(bw.z), bf_hi(bw.z), bf_lo(bw.w), bf_hi(bw.w)};
;                     const u32x4 pw = *(const GAS u32x4*)(pp + off + bj * HALF);
;                     const f32x4 p0 = {bf_lo(pw.x), bf_hi(pw.x), bf_lo(pw.y), bf_hi(pw.y)}, p1 = {bf_lo(pw.z), bf_hi(pw.z), bf_lo(pw.w), bf_hi(pw.w)};
;                     const f32x4 z0 = acc[ai][bj][m][0] + bv[bj][0], z1 = acc[ai][bj][m][1] + bv[bj][1]; f32x4 g0, g1;
; #pragma unroll
;                     for (int i = 0; i < 4; ++i) { g0[i] = __builtin_amdgcn_rcpf(1.f + __expf(-z0[i])); g1[i] = __builtin_amdgcn_rcpf(1.f + __expf(-z1[i])); }
;                     const f32x4 o0 = b0 + g0 * p0, o1 = b1 + g1 * p1;
;                     if (out) { *(GAS f32x4*)(out + off + bj * HALF) = o0; *(GAS f32x4*)(out + off + bj * HALF + 4) = o1; }
;                     if (xb) { q[ai][m] += (o0[0] * o0[0] + o0[1] * o0[1]) + (o0[2] * o0[2] + o0[3] * o0[3]) + (o1[0] * o1[0] + o1[1] * o1[1]) + (o1[2] * o1[2] + o1[3] * o1[3]);
;                         u32x4 w; w.x = cvt_pk_bf16(o0[0], o0[1]); w.y = cvt_pk_bf16(o0[2], o0[3]); w.z = cvt_pk_bf16(o1[0], o1[1]); w.w = cvt_pk_bf16(o1[2], o1[3]); *(GAS u32x4*)(xb + off + bj * HALF) = w; } } }
;         if (xb) ssq_commit(ssq, q, row0, fr, fq);
	v_mov_b32_e32 v174, v200
	v_mov_b32_e32 v175, v201
	v_mov_b32_e32 v176, v202
	v_mov_b32_e32 v177, v203
	v_mov_b32_e32 v178, v204
	v_mov_b32_e32 v179, v205
	v_mov_b32_e32 v180, v206
	v_mov_b32_e32 v181, v207
	s_add_u32 vcc_lo, s34, 0x90000
	s_addc_u32 vcc_hi, s35, 0
	global_load_dwordx4 v[200:203], v156, vcc
	s_add_u32 vcc_lo, s30, 0x90000
	s_addc_u32 vcc_hi, s31, 0
	global_load_dwordx4 v[204:207], v156, vcc
	v_lshlrev_b32_e32 v86, 16, v174
	v_and_b32_e32 v87, 0xffff0000, v174
	v_lshlrev_b32_e32 v170, 16, v175
	v_and_b32_e32 v171, 0xffff0000, v175
	v_lshlrev_b32_e32 v172, 16, v176
	v_and_b32_e32 v173, 0xffff0000, v176
	v_lshlrev_b32_e32 v174, 16, v177
	v_and_b32_e32 v175, 0xffff0000, v177
	v_lshlrev_b32_e32 v176, 16, v178
	v_and_b32_e32 v177, 0xffff0000, v178
	v_lshlrev_b32_e32 v178, 16, v179
	v_and_b32_e32 v179, 0xffff0000, v179
	v_lshlrev_b32_e32 v188, 16, v180
	v_and_b32_e32 v189, 0xffff0000, v180
	v_lshlrev_b32_e32 v180, 16, v181
	v_and_b32_e32 v181, 0xffff0000, v181
	v_pk_fma_f32 v[84:85], v[84:85], v[178:179], v[170:171]
	v_pk_fma_f32 v[86:87], v[80:81], v[176:177], v[86:87]
	v_pk_fma_f32 v[80:81], v[182:183], v[180:181], v[174:175]
	v_pk_fma_f32 v[82:83], v[82:83], v[188:189], v[172:173]
	v_cvt_pk_bf16_f32 v170, v86, v87
	v_cvt_pk_bf16_f32 v171, v84, v85
	v_add_f32_e32 v178, 1.0, v78
	v_cvt_pk_bf16_f32 v172, v82, v83
	v_cvt_pk_bf16_f32 v173, v80, v81
	global_store_dwordx4 v[158:159], v[170:173], off offset:256
	s_nop 3
	v_lshl_add_u64 v[158:159], s[30:31], 0, v[160:161]
	v_add_f32_e32 v179, 1.0, v74
	v_add_f32_e32 v180, 1.0, v79
	v_add_f32_e32 v181, 1.0, v75
	v_rcp_f32_e32 v74, v76
	v_rcp_f32_e32 v78, v72
	v_rcp_f32_e32 v75, v77
	v_rcp_f32_e32 v79, v73
	v_rcp_f32_e32 v72, v178
	v_rcp_f32_e32 v178, v179
	v_rcp_f32_e32 v73, v180
	v_rcp_f32_e32 v179, v181
	v_rcp_f32_e32 v5, v25
	v_mul_f32_e32 v25, v141, v141
	v_fmac_f32_e32 v24, v142, v142
	v_add_f32_e32 v2, v2, v3
	v_fmac_f32_e32 v25, v140, v140
	v_add_f32_e32 v2, v24, v2
	v_mul_f32_e32 v3, v133, v133
	v_mul_f32_e32 v24, v129, v129
	v_add_f32_e32 v2, v25, v2
	v_mul_f32_e32 v25, v135, v135
	v_fmac_f32_e32 v3, v132, v132
	v_fmac_f32_e32 v24, v128, v128
	v_mul_f32_e32 v28, v131, v131
	v_fmac_f32_e32 v25, v134, v134
	v_add_f32_e32 v3, v3, v24
	v_fmac_f32_e32 v28, v130, v130
	v_add_f32_e32 v3, v25, v3
	v_add_f32_e32 v3, v28, v3
	v_add_f32_e32 v6, v6, v30
	v_add_f32_e32 v7, v7, v31
	v_add_f32_e32 v24, v2, v3
	v_mul_f32_e32 v6, 0xbfb8aa3b, v6
	v_mul_f32_e32 v7, 0xbfb8aa3b, v7
	ds_bpermute_b32 v25, v166, v24
	v_exp_f32_e32 v6, v6
	v_exp_f32_e32 v7, v7
	v_rcp_f32_e32 v28, v26
	v_rcp_f32_e32 v29, v27
	v_add_f32_e32 v6, 1.0, v6
	v_add_f32_e32 v7, 1.0, v7
	s_waitcnt lgkmcnt(0)
	v_add_f32_e32 v26, v24, v25
	v_rcp_f32_e32 v2, v6
	v_rcp_f32_e32 v3, v7
	ds_bpermute_b32 v27, v167, v26
	s_waitcnt vmcnt(7)
	v_mov_b32_e32 v170, v208
	v_mov_b32_e32 v171, v209
	v_mov_b32_e32 v172, v210
	v_mov_b32_e32 v173, v211
	v_mov_b32_e32 v174, v212
	v_mov_b32_e32 v175, v213
	v_mov_b32_e32 v176, v214
	v_mov_b32_e32 v177, v215
	s_add_u32 vcc_lo, s34, 0x90000
	s_addc_u32 vcc_hi, s35, 0
	global_load_dwordx4 v[208:211], v156, vcc offset:256
	s_add_u32 vcc_lo, s30, 0x90000
	s_addc_u32 vcc_hi, s31, 0
	global_load_dwordx4 v[212:215], v156, vcc offset:256
	v_lshlrev_b32_e32 v76, 16, v170
	v_and_b32_e32 v77, 0xffff0000, v170
	v_lshlrev_b32_e32 v170, 16, v171
	v_and_b32_e32 v171, 0xffff0000, v171
	v_lshlrev_b32_e32 v180, 16, v172
	v_and_b32_e32 v181, 0xffff0000, v172
	v_lshlrev_b32_e32 v172, 16, v173
	v_and_b32_e32 v173, 0xffff0000, v173
	v_lshlrev_b32_e32 v182, 16, v174
	v_and_b32_e32 v183, 0xffff0000, v174
	v_lshlrev_b32_e32 v174, 16, v175
	v_and_b32_e32 v175, 0xffff0000, v175
	v_lshlrev_b32_e32 v188, 16, v176
	v_and_b32_e32 v189, 0xffff0000, v176
	v_lshlrev_b32_e32 v176, 16, v177
	v_and_b32_e32 v177, 0xffff0000, v177
	v_pk_fma_f32 v[72:73], v[72:73], v[174:175], v[170:171]
	v_pk_fma_f32 v[76:77], v[74:75], v[182:183], v[76:77]
	v_pk_fma_f32 v[74:75], v[178:179], v[176:177], v[172:173]
	v_pk_fma_f32 v[78:79], v[78:79], v[188:189], v[180:181]
	v_cvt_pk_bf16_f32 v170, v76, v77
	v_cvt_pk_bf16_f32 v171, v72, v73
	v_lshl_add_u64 v[182:183], s[96:97], 0, v[160:161]
	v_cvt_pk_bf16_f32 v172, v78, v79
	v_cvt_pk_bf16_f32 v173, v74, v75
	v_add_f32_e32 v160, 1.0, v64
	v_add_f32_e32 v161, 1.0, v65
	v_add_f32_e32 v162, 1.0, v66
	v_add_f32_e32 v163, 1.0, v67
	v_rcp_f32_e32 v64, v68
	v_rcp_f32_e32 v66, v160
	v_rcp_f32_e32 v65, v69
	v_rcp_f32_e32 v67, v161
	v_rcp_f32_e32 v68, v70
	v_rcp_f32_e32 v160, v162
	v_rcp_f32_e32 v69, v71
	v_rcp_f32_e32 v161, v163
	v_lshl_add_u64 v[158:159], v[156:157], 0, s[58:59]
	global_store_dwordx4 v[182:183], v[170:173], off
	s_nop 3
	v_lshl_add_u64 v[188:189], s[34:35], 0, v[158:159]
	s_waitcnt vmcnt(7)
; #define GAS __attribute__((address_space(1)))
; __device__ __forceinline__ unsigned cvt_pk_bf16(float lo, float hi) { unsigned r; asm volatile("v_cvt_pk_bf16_f32 %0, %1, %2" : "=v"(r) : "v"(lo), "v"(hi)); return r; }
; __device__ __forceinline__ float bf_lo(unsigned w) { return __uint_as_float(w << 16); }
; __device__ __forceinline__ float bf_hi(unsigned w) { return __uint_as_float(w & 0xffff0000u); }
;     __device__ __forceinline__ void operator()(const f32x4 (&acc)[2][2][4][2], const Unit& u, int wr, int wc, int fr, int fq) const {
;     ...
;             for (int m = 0; m < 4; ++m) { const size_t off = (size_t)(row0 + ai * HALF + m * 16) * DM + col0; q[ai][m] = 0.f;
; #pragma unroll
;                 for (int bj = 0; bj < 2; ++bj) { const u32x4 bw = *(const GAS u32x4*)(baseb + off + bj * HALF);
;                     const f32x4 b0 = {bf_lo(bw.x), bf_hi(bw.x), bf_lo(bw.y), bf_hi(bw.y)}, b1 = {bf_lo(bw.z), bf_hi(bw.z), bf_lo(bw.w), bf_hi(bw.w)};
;                     const u32x4 pw = *(const GAS u32x4*)(pp + off + bj * HALF);
;                     const f32x4 p0 = {bf_lo(pw.x), bf_hi(pw.x), bf_lo(pw.y), bf_hi(pw.y)}, p1 = {bf_lo(pw.z), bf_hi(pw.z), bf_lo(pw.w), bf_hi(pw.w)};
;                     const f32x4 z0 = acc[ai][bj][m][0] + bv[bj][0], z1 = acc[ai][bj][m][1] + bv[bj][1]; f32x4 g0, g1;
; #pragma unroll
;                     for (int i = 0; i < 4; ++i) { g0[i] = __builtin_amdgcn_rcpf(1.f + __expf(-z0[i])); g1[i] = __builtin_amdgcn_rcpf(1.f + __expf(-z1[i])); }
;                     const f32x4 o0 = b0 + g0 * p0, o1 = b1 + g1 * p1;
;                     if (out) { *(GAS f32x4*)(out + off + bj * HALF) = o0; *(GAS f32x4*)(out + off + bj * HALF + 4) = o1; }
;                     if (xb) { q[ai][m] += (o0[0] * o0[0] + o0[1] * o0[1]) + (o0[2] * o0[2] + o0[3] * o0[3]) + (o1[0] * o1[0] + o1[1] * o1[1]) + (o1[2] * o1[2] + o1[3] * o1[3]);
;                         u32x4 w; w.x = cvt_pk_bf16(o0[0], o0[1]); w.y = cvt_pk_bf16(o0[2], o0[3]); w.z = cvt_pk_bf16(o1[0], o1[1]); w.w = cvt_pk_bf16(o1[2], o1[3]); *(GAS u32x4*)(xb + off + bj * HALF) = w; } } }
	v_mov_b32_e32 v174, v192
	v_mov_b32_e32 v175, v193
	v_mov_b32_e32 v176, v194
	v_mov_b32_e32 v177, v195
	v_mov_b32_e32 v178, v196
	v_mov_b32_e32 v179, v197
	v_mov_b32_e32 v180, v198
	v_mov_b32_e32 v181, v199
	s_add_u32 vcc_lo, s34, 0xa0000
	s_addc_u32 vcc_hi, s35, 0
	global_load_dwordx4 v[192:195], v156, vcc
	s_add_u32 vcc_lo, s30, 0xa0000
	s_addc_u32 vcc_hi, s31, 0
	global_load_dwordx4 v[196:199], v156, vcc
	v_lshlrev_b32_e32 v70, 16, v174
	v_and_b32_e32 v71, 0xffff0000, v174
	v_lshlrev_b32_e32 v162, 16, v175
	v_and_b32_e32 v163, 0xffff0000, v175
	v_lshlrev_b32_e32 v170, 16, v176
	v_and_b32_e32 v171, 0xffff0000, v176
	v_lshlrev_b32_e32 v172, 16, v177
	v_and_b32_e32 v173, 0xffff0000, v177
	v_lshlrev_b32_e32 v174, 16, v178
	v_and_b32_e32 v175, 0xffff0000, v178
	v_lshlrev_b32_e32 v176, 16, v179
	v_and_b32_e32 v177, 0xffff0000, v179
	v_lshlrev_b32_e32 v178, 16, v180
	v_and_b32_e32 v179, 0xffff0000, v180
	v_lshlrev_b32_e32 v180, 16, v181
	v_and_b32_e32 v181, 0xffff0000, v181
	v_pk_fma_f32 v[68:69], v[68:69], v[176:177], v[162:163]
	v_pk_fma_f32 v[70:71], v[64:65], v[174:175], v[70:71]
	v_pk_fma_f32 v[64:65], v[160:161], v[180:181], v[172:173]
	v_pk_fma_f32 v[66:67], v[66:67], v[178:179], v[170:171]
	v_cvt_pk_bf16_f32 v160, v70, v71
	v_cvt_pk_bf16_f32 v161, v68, v69
	v_lshl_add_u64 v[178:179], s[30:31], 0, v[158:159]
	v_cvt_pk_bf16_f32 v162, v66, v67
	v_cvt_pk_bf16_f32 v163, v64, v65
	global_store_dwordx4 v[182:183], v[160:163], off offset:256
	s_nop 3
	v_add_f32_e32 v174, 1.0, v62
	v_add_f32_e32 v175, 1.0, v58
	v_add_f32_e32 v176, 1.0, v63
	v_add_f32_e32 v177, 1.0, v59
	v_rcp_f32_e32 v58, v60
	v_rcp_f32_e32 v62, v56
	v_rcp_f32_e32 v59, v61
	v_rcp_f32_e32 v63, v57
	v_rcp_f32_e32 v56, v174
	v_rcp_f32_e32 v174, v175
	v_rcp_f32_e32 v57, v176
	v_rcp_f32_e32 v175, v177
	v_lshl_add_u64 v[158:159], s[96:97], 0, v[158:159]
	s_waitcnt vmcnt(7)
	v_mov_b32_e32 v160, v200
	v_mov_b32_e32 v161, v201
	v_mov_b32_e32 v162, v202
	v_mov_b32_e32 v163, v203
	v_mov_b32_e32 v170, v204
	v_mov_b32_e32 v171, v205
	v_mov_b32_e32 v172, v206
	v_mov_b32_e32 v173, v207
	s_add_u32 vcc_lo, s34, 0xa0000
	s_addc_u32 vcc_hi, s35, 0
	global_load_dwordx4 v[200:203], v156, vcc offset:256
	s_add_u32 vcc_lo, s30, 0xa0000
	s_addc_u32 vcc_hi, s31, 0
	global_load_dwordx4 v[204:207], v156, vcc offset:256
	v_lshlrev_b32_e32 v60, 16, v160
	v_and_b32_e32 v61, 0xffff0000, v160
	v_lshlrev_b32_e32 v160, 16, v161
	v_and_b32_e32 v161, 0xffff0000, v161
	v_lshlrev_b32_e32 v176, 16, v162
	v_and_b32_e32 v177, 0xffff0000, v162
	v_lshlrev_b32_e32 v162, 16, v163
	v_and_b32_e32 v163, 0xffff0000, v163
	v_lshlrev_b32_e32 v180, 16, v170
	v_and_b32_e32 v181, 0xffff0000, v170
	v_lshlrev_b32_e32 v170, 16, v171
	v_and_b32_e32 v171, 0xffff0000, v171
	v_lshlrev_b32_e32 v182, 16, v172
	v_and_b32_e32 v183, 0xffff0000, v172
	v_lshlrev_b32_e32 v172, 16, v173
	v_and_b32_e32 v173, 0xffff0000, v173
	v_pk_fma_f32 v[56:57], v[56:57], v[170:171], v[160:161]
	v_pk_fma_f32 v[60:61], v[58:59], v[180:181], v[60:61]
	v_pk_fma_f32 v[58:59], v[174:175], v[172:173], v[162:163]
	v_pk_fma_f32 v[62:63], v[62:63], v[182:183], v[176:177]
	v_cvt_pk_bf16_f32 v170, v60, v61
	v_cvt_pk_bf16_f32 v171, v56, v57
	v_add_f32_e32 v182, 1.0, v48
	v_cvt_pk_bf16_f32 v172, v62, v63
	v_cvt_pk_bf16_f32 v173, v58, v59
	s_nop 0
	v_add_f32_e32 v183, 1.0, v49
	v_rcp_f32_e32 v48, v52
	v_rcp_f32_e32 v50, v182
	v_rcp_f32_e32 v49, v53
	v_rcp_f32_e32 v51, v183
	v_rcp_f32_e32 v52, v54
	v_rcp_f32_e32 v182, v186
	v_rcp_f32_e32 v53, v55
	v_rcp_f32_e32 v183, v187
	v_lshl_add_u64 v[160:161], v[156:157], 0, s[40:41]
	global_store_dwordx4 v[158:159], v[170:173], off
	s_nop 3
	v_lshl_add_u64 v[162:163], s[34:35], 0, v[160:161]
	s_mov_b64 s[40:41], 0xb0000
	s_waitcnt vmcnt(7)
	v_mov_b32_e32 v174, v208
	v_mov_b32_e32 v175, v209
	v_mov_b32_e32 v176, v210
	v_mov_b32_e32 v177, v211
	v_mov_b32_e32 v178, v212
	v_mov_b32_e32 v179, v213
	v_mov_b32_e32 v180, v214
	v_mov_b32_e32 v181, v215
	s_add_u32 vcc_lo, s34, 0xb0000
	s_addc_u32 vcc_hi, s35, 0
	global_load_dwordx4 v[208:211], v156, vcc
	s_add_u32 vcc_lo, s30, 0xb0000
	s_addc_u32 vcc_hi, s31, 0
	global_load_dwordx4 v[212:215], v156, vcc
	v_lshlrev_b32_e32 v54, 16, v174
	v_and_b32_e32 v55, 0xffff0000, v174
	v_lshlrev_b32_e32 v170, 16, v175
	v_and_b32_e32 v171, 0xffff0000, v175
	v_lshlrev_b32_e32 v172, 16, v176
	v_and_b32_e32 v173, 0xffff0000, v176
	v_lshlrev_b32_e32 v174, 16, v177
	v_and_b32_e32 v175, 0xffff0000, v177
	v_lshlrev_b32_e32 v176, 16, v178
	v_and_b32_e32 v177, 0xffff0000, v178
	v_lshlrev_b32_e32 v178, 16, v179
	v_and_b32_e32 v179, 0xffff0000, v179
	v_lshlrev_b32_e32 v188, 16, v180
	v_and_b32_e32 v189, 0xffff0000, v180
	v_lshlrev_b32_e32 v180, 16, v181
	v_and_b32_e32 v181, 0xffff0000, v181
	v_pk_fma_f32 v[52:53], v[52:53], v[178:179], v[170:171]
	v_pk_fma_f32 v[54:55], v[48:49], v[176:177], v[54:55]
	v_pk_fma_f32 v[48:49], v[182:183], v[180:181], v[174:175]
	v_pk_fma_f32 v[50:51], v[50:51], v[188:189], v[172:173]
	v_cvt_pk_bf16_f32 v170, v54, v55
	v_cvt_pk_bf16_f32 v171, v52, v53
	v_add_f32_e32 v178, 1.0, v38
	v_cvt_pk_bf16_f32 v172, v50, v51
	v_cvt_pk_bf16_f32 v173, v48, v49
	global_store_dwordx4 v[158:159], v[170:173], off offset:256
	s_nop 3
	v_lshl_add_u64 v[158:159], s[30:31], 0, v[160:161]
	v_add_f32_e32 v179, 1.0, v34
	v_add_f32_e32 v180, 1.0, v39
	v_add_f32_e32 v181, 1.0, v35
	v_rcp_f32_e32 v34, v36
	v_rcp_f32_e32 v38, v32
	v_rcp_f32_e32 v35, v37
	v_rcp_f32_e32 v39, v33
	v_rcp_f32_e32 v32, v178
	v_rcp_f32_e32 v178, v179
	v_rcp_f32_e32 v33, v180
	v_rcp_f32_e32 v179, v181
	v_lshl_add_u64 v[160:161], s[96:97], 0, v[160:161]
	s_waitcnt vmcnt(7)
; #define GAS __attribute__((address_space(1)))
; __device__ __forceinline__ float bf_lo(unsigned w) { return __uint_as_float(w << 16); }
; __device__ __forceinline__ void ssq_commit(u64_t* ssq, float (&q)[2][4], int row0, int fr, int fq) {
;     const int lane = fq * 16 + fr;
; #pragma unroll
;     for (int ai = 0; ai < 2; ++ai)
; #pragma unroll
;         for (int m = 0; m < 4; ++m) { float v = q[ai][m];
;             v += __int_as_float(__builtin_amdgcn_ds_bpermute((lane ^ 16) << 2, __float_as_int(v)));
;             v += __int_as_float(__builtin_amdgcn_ds_bpermute((lane ^ 32) << 2, __float_as_int(v)));
;             if (fq == 0) __hip_atomic_fetch_add(ssq + row0 + ai * HALF + m * 16, (u64_t)(v * SSQ_FX + 0.5f), __ATOMIC_RELAXED, __HIP_MEMORY_SCOPE_AGENT); }
;     __device__ __forceinline__ void operator()(const f32x4 (&acc)[2][2][4][2], const Unit& u, int wr, int wc, int fr, int fq) const {
;     ...
;                 for (int bj = 0; bj < 2; ++bj) { const u32x4 bw = *(const GAS u32x4*)(baseb + off + bj * HALF);
;                     const f32x4 b0 = {bf_lo(bw.x), bf_hi(bw.x), bf_lo(bw.y), bf_hi(bw.y)}, b1 = {bf_lo(bw.z), bf_hi(bw.z), bf_lo(bw.w), bf_hi(bw.w)};
;                     const u32x4 pw = *(const GAS u32x4*)(pp + off + bj * HALF);
;                     const f32x4 p0 = {bf_lo(pw.x), bf_hi(pw.x), bf_lo(pw.y), bf_hi(pw.y)}, p1 = {bf_lo(pw.z), bf_hi(pw.z), bf_lo(pw.w), bf_hi(pw.w)};
;                     const f32x4 z0 = acc[ai][bj][m][0] + bv[bj][0], z1 = acc[ai][bj][m][1] + bv[bj][1]; f32x4 g0, g1;
; #pragma unroll
;                     for (int i = 0; i < 4; ++i) { g0[i] = __builtin_amdgcn_rcpf(1.f + __expf(-z0[i])); g1[i] = __builtin_amdgcn_rcpf(1.f + __expf(-z1[i])); }
;                     const f32x4 o0 = b0 + g0 * p0, o1 = b1 + g1 * p1;
;                     if (out) { *(GAS f32x4*)(out + off + bj * HALF) = o0; *(GAS f32x4*)(out + off + bj * HALF + 4) = o1; }
;                     if (xb) { q[ai][m] += (o0[0] * o0[0] + o0[1] * o0[1]) + (o0[2] * o0[2] + o0[3] * o0[3]) + (o1[0] * o1[0] + o1[1] * o1[1]) + (o1[2] * o1[2] + o1[3] * o1[3]);
;                         u32x4 w; w.x = cvt_pk_bf16(o0[0], o0[1]); w.y = cvt_pk_bf16(o0[2], o0[3]); w.z = cvt_pk_bf16(o1[0], o1[1]); w.w = cvt_pk_bf16(o1[2], o1[3]); *(GAS u32x4*)(xb + off + bj * HALF) = w; } } }
;         if (xb) ssq_commit(ssq, q, row0, fr, fq);
	v_mov_b32_e32 v170, v192
	v_mov_b32_e32 v171, v193
	v_mov_b32_e32 v172, v194
	v_mov_b32_e32 v173, v195
	v_mov_b32_e32 v174, v196
	v_mov_b32_e32 v175, v197
	v_mov_b32_e32 v176, v198
	v_mov_b32_e32 v177, v199
	s_add_u32 vcc_lo, s34, 0xb0000
	s_addc_u32 vcc_hi, s35, 0
	global_load_dwordx4 v[192:195], v156, vcc offset:256
	s_add_u32 vcc_lo, s30, 0xb0000
	s_addc_u32 vcc_hi, s31, 0
	global_load_dwordx4 v[196:199], v156, vcc offset:256
	v_lshlrev_b32_e32 v36, 16, v170
	v_and_b32_e32 v37, 0xffff0000, v170
	v_lshlrev_b32_e32 v170, 16, v171
	v_and_b32_e32 v171, 0xffff0000, v171
	v_lshlrev_b32_e32 v180, 16, v172
	v_and_b32_e32 v181, 0xffff0000, v172
	v_lshlrev_b32_e32 v172, 16, v173
	v_and_b32_e32 v173, 0xffff0000, v173
	v_lshlrev_b32_e32 v182, 16, v174
	v_and_b32_e32 v183, 0xffff0000, v174
	v_lshlrev_b32_e32 v174, 16, v175
	v_and_b32_e32 v175, 0xffff0000, v175
	v_lshlrev_b32_e32 v188, 16, v176
	v_and_b32_e32 v189, 0xffff0000, v176
	v_lshlrev_b32_e32 v176, 16, v177
	v_and_b32_e32 v177, 0xffff0000, v177
	v_pk_fma_f32 v[32:33], v[32:33], v[174:175], v[170:171]
	v_pk_fma_f32 v[36:37], v[34:35], v[182:183], v[36:37]
	v_pk_fma_f32 v[34:35], v[178:179], v[176:177], v[172:173]
	v_pk_fma_f32 v[38:39], v[38:39], v[188:189], v[180:181]
	v_cvt_pk_bf16_f32 v170, v36, v37
	v_cvt_pk_bf16_f32 v171, v32, v33
	v_lshl_add_u64 v[182:183], v[156:157], 0, s[40:41]
	v_cvt_pk_bf16_f32 v172, v38, v39
	v_cvt_pk_bf16_f32 v173, v34, v35
	v_add_f32_e32 v156, 1.0, v16
	v_add_f32_e32 v157, 1.0, v17
	v_add_f32_e32 v158, 1.0, v18
	v_add_f32_e32 v159, 1.0, v19
	v_rcp_f32_e32 v16, v20
	v_rcp_f32_e32 v18, v156
	v_rcp_f32_e32 v17, v21
	v_rcp_f32_e32 v19, v157
	v_rcp_f32_e32 v20, v22
	v_rcp_f32_e32 v156, v158
	v_rcp_f32_e32 v21, v23
	v_rcp_f32_e32 v157, v159
	global_store_dwordx4 v[160:161], v[170:173], off
	s_nop 3
	v_lshl_add_u64 v[188:189], s[34:35], 0, v[182:183]
	s_waitcnt vmcnt(7)
	v_mov_b32_e32 v174, v200
	v_mov_b32_e32 v175, v201
	v_mov_b32_e32 v176, v202
	v_mov_b32_e32 v177, v203
	v_mov_b32_e32 v178, v204
	v_mov_b32_e32 v179, v205
	v_mov_b32_e32 v180, v206
	v_mov_b32_e32 v181, v207
	v_lshlrev_b32_e32 v22, 16, v174
	v_and_b32_e32 v23, 0xffff0000, v174
	v_lshlrev_b32_e32 v158, 16, v175
	v_and_b32_e32 v159, 0xffff0000, v175
	v_lshlrev_b32_e32 v162, 16, v176
	v_and_b32_e32 v163, 0xffff0000, v176
	v_lshlrev_b32_e32 v170, 16, v177
	v_and_b32_e32 v171, 0xffff0000, v177
	v_lshlrev_b32_e32 v172, 16, v178
	v_and_b32_e32 v173, 0xffff0000, v178
	v_lshlrev_b32_e32 v174, 16, v179
	v_and_b32_e32 v175, 0xffff0000, v179
	v_lshlrev_b32_e32 v176, 16, v180
	v_and_b32_e32 v177, 0xffff0000, v180
	v_lshlrev_b32_e32 v178, 16, v181
	v_and_b32_e32 v179, 0xffff0000, v181
	v_pk_fma_f32 v[20:21], v[20:21], v[174:175], v[158:159]
	v_pk_fma_f32 v[22:23], v[16:17], v[172:173], v[22:23]
	v_pk_fma_f32 v[16:17], v[156:157], v[178:179], v[170:171]
	v_pk_fma_f32 v[18:19], v[18:19], v[176:177], v[162:163]
	v_cvt_pk_bf16_f32 v156, v22, v23
	v_cvt_pk_bf16_f32 v157, v20, v21
	v_lshl_add_u64 v[170:171], s[30:31], 0, v[182:183]
	v_cvt_pk_bf16_f32 v158, v18, v19
	v_cvt_pk_bf16_f32 v159, v16, v17
	global_store_dwordx4 v[160:161], v[156:159], off offset:256
	s_nop 3
	s_nop 0
	s_waitcnt vmcnt(5)
	v_mov_b32_e32 v156, v208
	v_mov_b32_e32 v157, v209
	v_mov_b32_e32 v158, v210
	v_mov_b32_e32 v159, v211
	v_mov_b32_e32 v160, v212
	v_mov_b32_e32 v161, v213
	v_mov_b32_e32 v162, v214
	v_mov_b32_e32 v163, v215
	v_lshlrev_b32_e32 v12, 16, v156
	v_and_b32_e32 v13, 0xffff0000, v156
	v_lshlrev_b32_e32 v42, 16, v157
	v_and_b32_e32 v43, 0xffff0000, v157
	v_lshlrev_b32_e32 v44, 16, v158
	v_and_b32_e32 v45, 0xffff0000, v158
	v_lshlrev_b32_e32 v46, 16, v159
	v_and_b32_e32 v47, 0xffff0000, v159
	v_lshlrev_b32_e32 v156, 16, v160
	v_and_b32_e32 v157, 0xffff0000, v160
	v_lshlrev_b32_e32 v158, 16, v161
	v_and_b32_e32 v159, 0xffff0000, v161
	v_lshlrev_b32_e32 v160, 16, v162
	v_and_b32_e32 v161, 0xffff0000, v162
	v_lshlrev_b32_e32 v162, 16, v163
	v_and_b32_e32 v163, 0xffff0000, v163
	v_pk_fma_f32 v[8:9], v[8:9], v[158:159], v[42:43]
	v_pk_fma_f32 v[12:13], v[10:11], v[156:157], v[12:13]
	v_pk_fma_f32 v[10:11], v[40:41], v[162:163], v[46:47]
	v_pk_fma_f32 v[14:15], v[14:15], v[160:161], v[44:45]
	v_cvt_pk_bf16_f32 v40, v12, v13
	v_cvt_pk_bf16_f32 v41, v8, v9
	v_lshl_add_u64 v[160:161], s[96:97], 0, v[182:183]
	v_cvt_pk_bf16_f32 v42, v14, v15
	v_cvt_pk_bf16_f32 v43, v10, v11
	s_waitcnt vmcnt(2)
	v_mov_b32_e32 v44, v192
	v_mov_b32_e32 v45, v193
	v_mov_b32_e32 v46, v194
	v_mov_b32_e32 v47, v195
	v_mov_b32_e32 v156, v196
	v_mov_b32_e32 v157, v197
	v_mov_b32_e32 v158, v198
	v_mov_b32_e32 v159, v199
	v_lshlrev_b32_e32 v24, 16, v44
	global_store_dwordx4 v[160:161], v[40:43], off
	s_nop 3
	v_and_b32_e32 v25, 0xffff0000, v44
	v_lshlrev_b32_e32 v6, 16, v45
	v_and_b32_e32 v7, 0xffff0000, v45
	v_lshlrev_b32_e32 v30, 16, v46
	v_and_b32_e32 v31, 0xffff0000, v46
	v_lshlrev_b32_e32 v40, 16, v47
	v_and_b32_e32 v41, 0xffff0000, v47
	v_lshlrev_b32_e32 v42, 16, v156
	v_and_b32_e32 v43, 0xffff0000, v156
	v_lshlrev_b32_e32 v44, 16, v157
	v_and_b32_e32 v45, 0xffff0000, v157
	v_lshlrev_b32_e32 v46, 16, v158
	v_and_b32_e32 v47, 0xffff0000, v158
	v_lshlrev_b32_e32 v128, 16, v159
	v_and_b32_e32 v129, 0xffff0000, v159
	v_pk_fma_f32 v[6:7], v[2:3], v[44:45], v[6:7]
	v_pk_fma_f32 v[24:25], v[0:1], v[42:43], v[24:25]
	v_pk_fma_f32 v[2:3], v[28:29], v[128:129], v[40:41]
	v_pk_fma_f32 v[4:5], v[4:5], v[46:47], v[30:31]
	v_lshl_add_u64 v[0:1], v[154:155], 3, s[76:77]
	v_cvt_pk_bf16_f32 v28, v24, v25
	v_cvt_pk_bf16_f32 v29, v6, v7
	v_cvt_pk_bf16_f32 v30, v4, v5
	v_cvt_pk_bf16_f32 v31, v2, v3
	global_store_dwordx4 v[160:161], v[28:31], off offset:256
	s_nop 3
	s_and_saveexec_b64 s[40:41], s[36:37]
	s_cbranch_execz .LBB0_896
	s_waitcnt lgkmcnt(0)
	v_add_f32_e32 v26, v26, v27
	v_fma_f32 v26, v26, s74, 0.5
	v_trunc_f32_e32 v26, v26
	v_mul_f32_e32 v27, 0x2f800000, v26
	v_floor_f32_e32 v27, v27
	v_fmac_f32_e32 v26, 0xcf800000, v27
	v_cvt_u32_f32_e32 v26, v26
	v_cvt_u32_f32_e32 v27, v27
	flat_atomic_add_x2 v[0:1], v[26:27]
